# rwkv_finalize fast path: 16 units per wave with loads 3 units ahead, loop-invariant vectors hoisted
# baseline (speedup 1.0000x reference)
.LBB0_997:
	s_or_b64 exec, exec, s[0:1]
	s_waitcnt vmcnt(4)
	v_mov_b32_e32 v4, v178
	s_waitcnt lgkmcnt(0)
	s_barrier
	s_mov_b32 s0, 0x8000
	v_ashrrev_i32_e32 v2, 6, v4
	v_add_u32_e32 v0, s71, v2
	v_cmp_gt_i32_e32 vcc, s0, v0
	s_and_saveexec_b64 s[0:1], vcc
	v_readlane_b32 s42, v236, 44
	v_readlane_b32 s44, v235, 0
	v_readlane_b32 s46, v235, 2
	v_readlane_b32 s48, v234, 34
	v_readlane_b32 s50, v234, 36
	v_readlane_b32 s52, v234, 38
	v_readlane_b32 s43, v236, 45
	v_readlane_b32 s45, v235, 1
	v_readlane_b32 s47, v235, 3
	v_readlane_b32 s49, v234, 35
	v_readlane_b32 s51, v234, 37
	v_readlane_b32 s53, v234, 39
	s_cbranch_execz .LBB0_1000
	v_bfe_u32 v1, v4, 4, 2
	v_lshlrev_b32_e32 v4, 2, v4
	v_readlane_b32 s12, v235, 22
	v_and_b32_e32 v4, 60, v4
	s_mov_b64 s[40:41], 0
	v_lshl_add_u32 v5, v2, 2, s12
	s_cmpk_eq_u32 s70, 0x800
	s_cbranch_scc1 .Lff5_entry
.LBB0_999:
	v_and_or_b32 v2, v5, 4, v1
	v_ashrrev_i32_e32 v6, 1, v0
	v_mov_b64_e32 v[8:9], s[42:43]
	v_lshl_or_b32 v10, v2, 6, v4
	v_mov_b32_e32 v19, v3
	v_ashrrev_i32_e32 v7, 31, v6
	v_mad_i64_i32 v[14:15], s[12:13], v6, s78, v[8:9]
	v_lshlrev_b32_e32 v18, 1, v10
	v_lshlrev_b64 v[20:21], 11, v[6:7]
	v_lshlrev_b32_e32 v2, 2, v10
	v_lshlrev_b64 v[6:7], 10, v[6:7]
	v_lshl_add_u64 v[30:31], v[14:15], 0, v[18:19]
	v_lshl_add_u64 v[22:23], s[44:45], 0, v[20:21]
	v_lshl_add_u64 v[24:25], s[64:65], 0, v[6:7]
	v_lshl_add_u64 v[26:27], s[66:67], 0, v[6:7]
	v_lshl_add_u64 v[28:29], s[68:69], 0, v[6:7]
	global_load_dwordx4 v[6:9], v2, s[52:53]
	global_load_dwordx4 v[10:13], v2, s[48:49]
	v_lshl_add_u64 v[20:21], s[46:47], 0, v[20:21]
	global_load_dwordx2 v[30:31], v[30:31], off offset:3328
	v_lshl_add_u64 v[22:23], v[22:23], 0, v[2:3]
	v_lshl_add_u64 v[24:25], v[24:25], 0, v[18:19]
	v_lshl_add_u64 v[26:27], v[26:27], 0, v[18:19]
	global_load_dwordx4 v[14:17], v2, s[50:51]
	v_lshl_add_u64 v[28:29], v[28:29], 0, v[18:19]
	v_lshl_add_u64 v[32:33], v[20:21], 0, v[18:19]
	global_load_dwordx4 v[18:21], v[22:23], off
	s_nop 0
	global_load_dwordx2 v[22:23], v[24:25], off
	s_nop 0
	global_load_dwordx2 v[24:25], v[26:27], off
	s_nop 0
	global_load_dwordx2 v[26:27], v[28:29], off
	v_add_u32_e32 v0, s70, v0
	s_movk_i32 s12, 0x7fff
	v_cmp_lt_i32_e32 vcc, s12, v0
	s_or_b64 s[40:41], vcc, s[40:41]
	v_add_u32_e32 v5, s88, v5
	s_waitcnt vmcnt(5)
	v_lshlrev_b32_e32 v36, 16, v30
	v_and_b32_e32 v37, 0xffff0000, v30
	v_lshlrev_b32_e32 v38, 16, v31
	v_and_b32_e32 v39, 0xffff0000, v31
	s_waitcnt vmcnt(3)
	v_add_f32_e32 v2, v18, v19
	s_waitcnt vmcnt(2)
	v_lshlrev_b32_e32 v28, 16, v22
	v_and_b32_e32 v29, 0xffff0000, v22
	v_lshlrev_b32_e32 v22, 16, v23
	v_and_b32_e32 v23, 0xffff0000, v23
	s_waitcnt vmcnt(1)
	v_lshlrev_b32_e32 v30, 16, v24
	v_and_b32_e32 v31, 0xffff0000, v24
	v_lshlrev_b32_e32 v24, 16, v25
	v_and_b32_e32 v25, 0xffff0000, v25
	v_mul_f32_e32 v40, 0xbfb8aa3b, v36
	v_add_f32_e32 v2, v20, v2
	v_pk_mul_f32 v[28:29], v[28:29], v[30:31]
	v_pk_mul_f32 v[22:23], v[22:23], v[24:25]
	v_exp_f32_e32 v24, v40
	v_add_f32_e32 v2, v21, v2
	v_mul_f32_e32 v41, 0xbfb8aa3b, v37
	v_mul_f32_e32 v42, 0xbfb8aa3b, v38
	v_pk_mul_f32 v[6:7], v[6:7], v[28:29]
	v_add_f32_dpp v2, v2, v2 quad_perm:[1,0,3,2] row_mask:0xf bank_mask:0xf bound_ctrl:1
	v_exp_f32_e32 v25, v41
	v_exp_f32_e32 v30, v42
	v_pk_mul_f32 v[8:9], v[8:9], v[22:23]
	v_add_f32_e32 v6, v6, v7
	v_add_f32_dpp v2, v2, v2 quad_perm:[2,3,0,1] row_mask:0xf bank_mask:0xf bound_ctrl:1
	v_add_f32_e32 v6, v8, v6
	v_add_f32_e32 v6, v9, v6
	v_add_f32_dpp v2, v2, v2 row_half_mirror row_mask:0xf bank_mask:0xf bound_ctrl:1
	v_add_f32_e32 v7, 1.0, v24
	v_add_f32_dpp v23, v6, v6 quad_perm:[1,0,3,2] row_mask:0xf bank_mask:0xf bound_ctrl:1
	v_add_f32_dpp v2, v2, v2 row_mirror row_mask:0xf bank_mask:0xf bound_ctrl:1
	v_rcp_f32_e32 v24, v7
	v_fmamk_f32 v7, v2, 0xbc800000, v19
	v_fmamk_f32 v6, v2, 0xbc800000, v18
	v_add_f32_e32 v8, 1.0, v25
	v_add_f32_e32 v9, 1.0, v30
	v_fmamk_f32 v21, v2, 0xbc800000, v21
	v_fmac_f32_e32 v20, 0xbc800000, v2
	v_pk_mul_f32 v[18:19], v[6:7], v[6:7]
	v_rcp_f32_e32 v25, v8
	v_rcp_f32_e32 v28, v9
	v_pk_mul_f32 v[8:9], v[20:21], v[20:21]
	v_add_f32_e32 v18, v18, v19
	v_add_f32_e32 v8, v8, v18
	v_add_f32_e32 v8, v9, v8
	v_mul_f32_e32 v43, 0xbfb8aa3b, v39
	v_exp_f32_e32 v31, v43
	v_add_f32_dpp v8, v8, v8 quad_perm:[1,0,3,2] row_mask:0xf bank_mask:0xf bound_ctrl:1
	v_add_f32_dpp v2, v23, v23 quad_perm:[2,3,0,1] row_mask:0xf bank_mask:0xf bound_ctrl:1
	s_waitcnt vmcnt(0)
	v_lshlrev_b32_e32 v34, 16, v26
	v_add_f32_dpp v8, v8, v8 quad_perm:[2,3,0,1] row_mask:0xf bank_mask:0xf bound_ctrl:1
	v_add_f32_e32 v22, 1.0, v31
	v_rcp_f32_e32 v22, v22
	v_add_f32_dpp v8, v8, v8 row_half_mirror row_mask:0xf bank_mask:0xf bound_ctrl:1
	v_add_f32_dpp v2, v2, v2 row_half_mirror row_mask:0xf bank_mask:0xf bound_ctrl:1
	v_and_b32_e32 v35, 0xffff0000, v26
	v_add_f32_dpp v8, v8, v8 row_mirror row_mask:0xf bank_mask:0xf bound_ctrl:1
	v_fmamk_f32 v8, v8, 0x3c800000, v195
	v_mul_f32_e32 v9, 0x4b800000, v8
	v_cmp_gt_f32_e32 vcc, s98, v8
	v_lshlrev_b32_e32 v26, 16, v27
	v_and_b32_e32 v27, 0xffff0000, v27
	v_cndmask_b32_e32 v8, v8, v9, vcc
	v_rsq_f32_e32 v8, v8
	v_add_f32_dpp v2, v2, v2 row_mirror row_mask:0xf bank_mask:0xf bound_ctrl:1
	v_mul_f32_e32 v23, v24, v36
	v_mul_f32_e32 v24, v25, v37
	v_mul_f32_e32 v9, 0x45800000, v8
	v_cndmask_b32_e32 v8, v8, v9, vcc
	v_pk_mul_f32 v[18:19], v[20:21], v[8:9] op_sel_hi:[1,0]
	v_pk_mul_f32 v[6:7], v[6:7], v[8:9] op_sel_hi:[1,0]
	v_pk_fma_f32 v[8:9], v[12:13], v[18:19], v[16:17]
	v_pk_fma_f32 v[6:7], v[10:11], v[6:7], v[14:15]
	v_mul_f32_e32 v25, v28, v38
	v_pk_fma_f32 v[8:9], v[2:3], v[26:27], v[8:9] op_sel_hi:[0,1,1]
	v_pk_fma_f32 v[6:7], v[2:3], v[34:35], v[6:7] op_sel_hi:[0,1,1]
	v_mul_f32_e32 v22, v22, v39
	v_mul_f32_e32 v2, v23, v6
	v_mul_f32_e32 v6, v24, v7
	v_mul_f32_e32 v7, v25, v8
	v_mul_f32_e32 v8, v22, v9
	v_cvt_pk_bf16_f32 v6, v2, v6
	v_cvt_pk_bf16_f32 v7, v7, v8
	global_store_dwordx2 v[32:33], v[6:7], off
	s_andn2_b64 exec, exec, s[40:41]
	s_cbranch_execnz .LBB0_999
	s_branch .LBB0_1000
.Lff5_entry:
	s_nop 1
	v_readfirstlane_b32 s12, v0
	v_and_or_b32 v2, v5, 4, v1
	v_lshl_or_b32 v10, v2, 6, v4
	v_lshlrev_b32_e32 v100, 2, v10
	v_lshlrev_b32_e32 v101, 1, v10
	s_lshr_b32 s12, s12, 1
	s_lshl_b32 s13, s12, 11
	s_add_u32 s40, s44, s13
	s_addc_u32 s41, s45, 0
	s_add_u32 s62, s46, s13
	s_addc_u32 s63, s47, 0
	s_lshl_b32 s13, s12, 10
	s_add_u32 s54, s64, s13
	s_addc_u32 s55, s65, 0
	s_add_u32 s56, s66, s13
	s_addc_u32 s57, s67, 0
	s_add_u32 s58, s68, s13
	s_addc_u32 s59, s69, 0
	s_mul_i32 s13, s12, s78
	s_add_u32 s60, s42, s13
	s_addc_u32 s61, s43, 0
	global_load_dwordx4 v[104:107], v100, s[52:53]
	global_load_dwordx4 v[108:111], v100, s[48:49]
	global_load_dwordx4 v[112:115], v100, s[50:51]
	global_load_dwordx2 v[20:21], v101, s[60:61] offset:3328
	global_load_dwordx4 v[22:25], v100, s[40:41]
	global_load_dwordx2 v[26:27], v101, s[54:55]
	global_load_dwordx2 v[28:29], v101, s[56:57]
	global_load_dwordx2 v[30:31], v101, s[58:59]
	s_add_u32 s60, s60, 0x6c0000
	s_addc_u32 s61, s61, 0
	s_add_u32 s40, s40, 0x200000
	s_addc_u32 s41, s41, 0
	s_add_u32 s54, s54, 0x100000
	s_addc_u32 s55, s55, 0
	s_add_u32 s56, s56, 0x100000
	s_addc_u32 s57, s57, 0
	s_add_u32 s58, s58, 0x100000
	s_addc_u32 s59, s59, 0
	global_load_dwordx2 v[32:33], v101, s[60:61] offset:3328
	global_load_dwordx4 v[34:37], v100, s[40:41]
	global_load_dwordx2 v[38:39], v101, s[54:55]
	global_load_dwordx2 v[40:41], v101, s[56:57]
	global_load_dwordx2 v[42:43], v101, s[58:59]
	s_add_u32 s60, s60, 0x6c0000
	s_addc_u32 s61, s61, 0
	s_add_u32 s40, s40, 0x200000
	s_addc_u32 s41, s41, 0
	s_add_u32 s54, s54, 0x100000
	s_addc_u32 s55, s55, 0
	s_add_u32 s56, s56, 0x100000
	s_addc_u32 s57, s57, 0
	s_add_u32 s58, s58, 0x100000
	s_addc_u32 s59, s59, 0
	global_load_dwordx2 v[44:45], v101, s[60:61] offset:3328
	global_load_dwordx4 v[46:49], v100, s[40:41]
	global_load_dwordx2 v[50:51], v101, s[54:55]
	global_load_dwordx2 v[52:53], v101, s[56:57]
	global_load_dwordx2 v[54:55], v101, s[58:59]
	s_add_u32 s60, s60, 0x6c0000
	s_addc_u32 s61, s61, 0
	s_add_u32 s40, s40, 0x200000
	s_addc_u32 s41, s41, 0
	s_add_u32 s54, s54, 0x100000
	s_addc_u32 s55, s55, 0
	s_add_u32 s56, s56, 0x100000
	s_addc_u32 s57, s57, 0
	s_add_u32 s58, s58, 0x100000
	s_addc_u32 s59, s59, 0
	global_load_dwordx2 v[56:57], v101, s[60:61] offset:3328
	global_load_dwordx4 v[58:61], v100, s[40:41]
	global_load_dwordx2 v[62:63], v101, s[54:55]
	global_load_dwordx2 v[64:65], v101, s[56:57]
	global_load_dwordx2 v[66:67], v101, s[58:59]
	s_add_u32 s60, s60, 0x6c0000
	s_addc_u32 s61, s61, 0
	s_add_u32 s40, s40, 0x200000
	s_addc_u32 s41, s41, 0
	s_add_u32 s54, s54, 0x100000
	s_addc_u32 s55, s55, 0
	s_add_u32 s56, s56, 0x100000
	s_addc_u32 s57, s57, 0
	s_add_u32 s58, s58, 0x100000
	s_addc_u32 s59, s59, 0
	s_waitcnt vmcnt(15)
	v_lshlrev_b32_e32 v70, 16, v20
	v_and_b32_e32 v71, 0xffff0000, v20
	v_lshlrev_b32_e32 v72, 16, v21
	v_and_b32_e32 v73, 0xffff0000, v21
	v_add_f32_e32 v78, v22, v23
	v_lshlrev_b32_e32 v80, 16, v26
	v_and_b32_e32 v81, 0xffff0000, v26
	v_lshlrev_b32_e32 v82, 16, v27
	v_and_b32_e32 v83, 0xffff0000, v27
	v_lshlrev_b32_e32 v136, 16, v28
	v_and_b32_e32 v137, 0xffff0000, v28
	v_lshlrev_b32_e32 v138, 16, v29
	v_and_b32_e32 v139, 0xffff0000, v29
	v_mul_f32_e32 v74, 0xbfb8aa3b, v70
	v_add_f32_e32 v78, v24, v78
	v_pk_mul_f32 v[80:81], v[80:81], v[136:137]
	v_pk_mul_f32 v[82:83], v[82:83], v[138:139]
	v_exp_f32_e32 v74, v74
	v_add_f32_e32 v78, v25, v78
	v_mul_f32_e32 v75, 0xbfb8aa3b, v71
	v_mul_f32_e32 v76, 0xbfb8aa3b, v72
	v_mul_f32_e32 v77, 0xbfb8aa3b, v73
	v_pk_mul_f32 v[80:81], v[104:105], v[80:81]
	v_add_f32_dpp v78, v78, v78 quad_perm:[1,0,3,2] row_mask:0xf bank_mask:0xf bound_ctrl:1
	v_exp_f32_e32 v75, v75
	v_exp_f32_e32 v76, v76
	v_exp_f32_e32 v77, v77
	v_pk_mul_f32 v[82:83], v[106:107], v[82:83]
	v_add_f32_e32 v116, v80, v81
	v_add_f32_dpp v78, v78, v78 quad_perm:[2,3,0,1] row_mask:0xf bank_mask:0xf bound_ctrl:1
	v_add_f32_e32 v116, v82, v116
	v_add_f32_e32 v116, v83, v116
	v_add_f32_dpp v78, v78, v78 row_half_mirror row_mask:0xf bank_mask:0xf bound_ctrl:1
	v_add_f32_e32 v74, 1.0, v74
	v_add_f32_e32 v75, 1.0, v75
	v_add_f32_dpp v116, v116, v116 quad_perm:[1,0,3,2] row_mask:0xf bank_mask:0xf bound_ctrl:1
	v_add_f32_dpp v78, v78, v78 row_mirror row_mask:0xf bank_mask:0xf bound_ctrl:1
	v_rcp_f32_e32 v74, v74
	v_add_f32_e32 v76, 1.0, v76
	v_add_f32_e32 v77, 1.0, v77
	v_fmamk_f32 v119, v78, 0xbc800000, v23
	v_fmamk_f32 v118, v78, 0xbc800000, v22
	v_fmamk_f32 v121, v78, 0xbc800000, v25
	v_fmamk_f32 v120, v78, 0xbc800000, v24
	v_pk_mul_f32 v[122:123], v[118:119], v[118:119]
	v_rcp_f32_e32 v75, v75
	v_rcp_f32_e32 v76, v76
	v_rcp_f32_e32 v77, v77
	v_pk_mul_f32 v[124:125], v[120:121], v[120:121]
	v_add_f32_e32 v126, v122, v123
	v_add_f32_e32 v126, v124, v126
	v_add_f32_e32 v126, v125, v126
	v_add_f32_dpp v116, v116, v116 quad_perm:[2,3,0,1] row_mask:0xf bank_mask:0xf bound_ctrl:1
	v_lshlrev_b32_e32 v128, 16, v30
	v_and_b32_e32 v129, 0xffff0000, v30
	v_add_f32_dpp v126, v126, v126 quad_perm:[1,0,3,2] row_mask:0xf bank_mask:0xf bound_ctrl:1
	v_lshlrev_b32_e32 v130, 16, v31
	v_and_b32_e32 v131, 0xffff0000, v31
	v_add_f32_dpp v126, v126, v126 quad_perm:[2,3,0,1] row_mask:0xf bank_mask:0xf bound_ctrl:1
	v_add_f32_dpp v116, v116, v116 row_half_mirror row_mask:0xf bank_mask:0xf bound_ctrl:1
	v_mul_f32_e32 v70, v74, v70
	v_add_f32_dpp v126, v126, v126 row_half_mirror row_mask:0xf bank_mask:0xf bound_ctrl:1
	v_mul_f32_e32 v71, v75, v71
	v_mul_f32_e32 v72, v76, v72
	v_add_f32_dpp v126, v126, v126 row_mirror row_mask:0xf bank_mask:0xf bound_ctrl:1
	v_add_f32_dpp v116, v116, v116 row_mirror row_mask:0xf bank_mask:0xf bound_ctrl:1
	v_mul_f32_e32 v73, v77, v73
	v_fmamk_f32 v126, v126, 0x3c800000, v195
	v_mul_f32_e32 v127, 0x4b800000, v126
	v_cmp_gt_f32_e32 vcc, s98, v126
	s_nop 1
	v_cndmask_b32_e32 v126, v126, v127, vcc
	v_rsq_f32_e32 v126, v126
	s_nop 0
	v_mul_f32_e32 v127, 0x45800000, v126
	v_cndmask_b32_e32 v140, v126, v127, vcc
	v_pk_mul_f32 v[138:139], v[120:121], v[140:141] op_sel_hi:[1,0]
	v_pk_mul_f32 v[136:137], v[118:119], v[140:141] op_sel_hi:[1,0]
	v_pk_fma_f32 v[134:135], v[110:111], v[138:139], v[114:115]
	v_pk_fma_f32 v[132:133], v[108:109], v[136:137], v[112:113]
	v_pk_fma_f32 v[134:135], v[116:117], v[130:131], v[134:135] op_sel_hi:[0,1,1]
	v_pk_fma_f32 v[132:133], v[116:117], v[128:129], v[132:133] op_sel_hi:[0,1,1]
	v_mul_f32_e32 v132, v70, v132
	v_mul_f32_e32 v133, v71, v133
	v_mul_f32_e32 v134, v72, v134
	v_mul_f32_e32 v135, v73, v135
	v_cvt_pk_bf16_f32 v142, v132, v133
	v_cvt_pk_bf16_f32 v143, v134, v135
	global_store_dwordx2 v101, v[142:143], s[62:63]
	s_add_u32 s62, s62, 0x200000
	s_addc_u32 s63, s63, 0
	global_load_dwordx2 v[20:21], v101, s[60:61] offset:3328
	global_load_dwordx4 v[22:25], v100, s[40:41]
	global_load_dwordx2 v[26:27], v101, s[54:55]
	global_load_dwordx2 v[28:29], v101, s[56:57]
	global_load_dwordx2 v[30:31], v101, s[58:59]
	s_add_u32 s60, s60, 0x6c0000
	s_addc_u32 s61, s61, 0
	s_add_u32 s40, s40, 0x200000
	s_addc_u32 s41, s41, 0
	s_add_u32 s54, s54, 0x100000
	s_addc_u32 s55, s55, 0
	s_add_u32 s56, s56, 0x100000
	s_addc_u32 s57, s57, 0
	s_add_u32 s58, s58, 0x100000
	s_addc_u32 s59, s59, 0
	s_waitcnt vmcnt(16)
	v_lshlrev_b32_e32 v70, 16, v32
	v_and_b32_e32 v71, 0xffff0000, v32
	v_lshlrev_b32_e32 v72, 16, v33
	v_and_b32_e32 v73, 0xffff0000, v33
	v_add_f32_e32 v78, v34, v35
	v_lshlrev_b32_e32 v80, 16, v38
	v_and_b32_e32 v81, 0xffff0000, v38
	v_lshlrev_b32_e32 v82, 16, v39
	v_and_b32_e32 v83, 0xffff0000, v39
	v_lshlrev_b32_e32 v136, 16, v40
	v_and_b32_e32 v137, 0xffff0000, v40
	v_lshlrev_b32_e32 v138, 16, v41
	v_and_b32_e32 v139, 0xffff0000, v41
	v_mul_f32_e32 v74, 0xbfb8aa3b, v70
	v_add_f32_e32 v78, v36, v78
	v_pk_mul_f32 v[80:81], v[80:81], v[136:137]
	v_pk_mul_f32 v[82:83], v[82:83], v[138:139]
	v_exp_f32_e32 v74, v74
	v_add_f32_e32 v78, v37, v78
	v_mul_f32_e32 v75, 0xbfb8aa3b, v71
	v_mul_f32_e32 v76, 0xbfb8aa3b, v72
	v_mul_f32_e32 v77, 0xbfb8aa3b, v73
	v_pk_mul_f32 v[80:81], v[104:105], v[80:81]
	v_add_f32_dpp v78, v78, v78 quad_perm:[1,0,3,2] row_mask:0xf bank_mask:0xf bound_ctrl:1
	v_exp_f32_e32 v75, v75
	v_exp_f32_e32 v76, v76
	v_exp_f32_e32 v77, v77
	v_pk_mul_f32 v[82:83], v[106:107], v[82:83]
	v_add_f32_e32 v116, v80, v81
	v_add_f32_dpp v78, v78, v78 quad_perm:[2,3,0,1] row_mask:0xf bank_mask:0xf bound_ctrl:1
	v_add_f32_e32 v116, v82, v116
	v_add_f32_e32 v116, v83, v116
	v_add_f32_dpp v78, v78, v78 row_half_mirror row_mask:0xf bank_mask:0xf bound_ctrl:1
	v_add_f32_e32 v74, 1.0, v74
	v_add_f32_e32 v75, 1.0, v75
	v_add_f32_dpp v116, v116, v116 quad_perm:[1,0,3,2] row_mask:0xf bank_mask:0xf bound_ctrl:1
	v_add_f32_dpp v78, v78, v78 row_mirror row_mask:0xf bank_mask:0xf bound_ctrl:1
	v_rcp_f32_e32 v74, v74
	v_add_f32_e32 v76, 1.0, v76
	v_add_f32_e32 v77, 1.0, v77
	v_fmamk_f32 v119, v78, 0xbc800000, v35
	v_fmamk_f32 v118, v78, 0xbc800000, v34
	v_fmamk_f32 v121, v78, 0xbc800000, v37
	v_fmamk_f32 v120, v78, 0xbc800000, v36
	v_pk_mul_f32 v[122:123], v[118:119], v[118:119]
	v_rcp_f32_e32 v75, v75
	v_rcp_f32_e32 v76, v76
	v_rcp_f32_e32 v77, v77
	v_pk_mul_f32 v[124:125], v[120:121], v[120:121]
	v_add_f32_e32 v126, v122, v123
	v_add_f32_e32 v126, v124, v126
	v_add_f32_e32 v126, v125, v126
	v_add_f32_dpp v116, v116, v116 quad_perm:[2,3,0,1] row_mask:0xf bank_mask:0xf bound_ctrl:1
	v_lshlrev_b32_e32 v128, 16, v42
	v_and_b32_e32 v129, 0xffff0000, v42
	v_add_f32_dpp v126, v126, v126 quad_perm:[1,0,3,2] row_mask:0xf bank_mask:0xf bound_ctrl:1
	v_lshlrev_b32_e32 v130, 16, v43
	v_and_b32_e32 v131, 0xffff0000, v43
	v_add_f32_dpp v126, v126, v126 quad_perm:[2,3,0,1] row_mask:0xf bank_mask:0xf bound_ctrl:1
	v_add_f32_dpp v116, v116, v116 row_half_mirror row_mask:0xf bank_mask:0xf bound_ctrl:1
	v_mul_f32_e32 v70, v74, v70
	v_add_f32_dpp v126, v126, v126 row_half_mirror row_mask:0xf bank_mask:0xf bound_ctrl:1
	v_mul_f32_e32 v71, v75, v71
	v_mul_f32_e32 v72, v76, v72
	v_add_f32_dpp v126, v126, v126 row_mirror row_mask:0xf bank_mask:0xf bound_ctrl:1
	v_add_f32_dpp v116, v116, v116 row_mirror row_mask:0xf bank_mask:0xf bound_ctrl:1
	v_mul_f32_e32 v73, v77, v73
	v_fmamk_f32 v126, v126, 0x3c800000, v195
	v_mul_f32_e32 v127, 0x4b800000, v126
	v_cmp_gt_f32_e32 vcc, s98, v126
	s_nop 1
	v_cndmask_b32_e32 v126, v126, v127, vcc
	v_rsq_f32_e32 v126, v126
	s_nop 0
	v_mul_f32_e32 v127, 0x45800000, v126
	v_cndmask_b32_e32 v140, v126, v127, vcc
	v_pk_mul_f32 v[138:139], v[120:121], v[140:141] op_sel_hi:[1,0]
	v_pk_mul_f32 v[136:137], v[118:119], v[140:141] op_sel_hi:[1,0]
	v_pk_fma_f32 v[134:135], v[110:111], v[138:139], v[114:115]
	v_pk_fma_f32 v[132:133], v[108:109], v[136:137], v[112:113]
	v_pk_fma_f32 v[134:135], v[116:117], v[130:131], v[134:135] op_sel_hi:[0,1,1]
	v_pk_fma_f32 v[132:133], v[116:117], v[128:129], v[132:133] op_sel_hi:[0,1,1]
	v_mul_f32_e32 v132, v70, v132
	v_mul_f32_e32 v133, v71, v133
	v_mul_f32_e32 v134, v72, v134
	v_mul_f32_e32 v135, v73, v135
	v_cvt_pk_bf16_f32 v142, v132, v133
	v_cvt_pk_bf16_f32 v143, v134, v135
	global_store_dwordx2 v101, v[142:143], s[62:63]
	s_add_u32 s62, s62, 0x200000
	s_addc_u32 s63, s63, 0
	global_load_dwordx2 v[32:33], v101, s[60:61] offset:3328
	global_load_dwordx4 v[34:37], v100, s[40:41]
	global_load_dwordx2 v[38:39], v101, s[54:55]
	global_load_dwordx2 v[40:41], v101, s[56:57]
	global_load_dwordx2 v[42:43], v101, s[58:59]
	s_add_u32 s60, s60, 0x6c0000
	s_addc_u32 s61, s61, 0
	s_add_u32 s40, s40, 0x200000
	s_addc_u32 s41, s41, 0
	s_add_u32 s54, s54, 0x100000
	s_addc_u32 s55, s55, 0
	s_add_u32 s56, s56, 0x100000
	s_addc_u32 s57, s57, 0
	s_add_u32 s58, s58, 0x100000
	s_addc_u32 s59, s59, 0
	s_waitcnt vmcnt(17)
	v_lshlrev_b32_e32 v70, 16, v44
	v_and_b32_e32 v71, 0xffff0000, v44
	v_lshlrev_b32_e32 v72, 16, v45
	v_and_b32_e32 v73, 0xffff0000, v45
	v_add_f32_e32 v78, v46, v47
	v_lshlrev_b32_e32 v80, 16, v50
	v_and_b32_e32 v81, 0xffff0000, v50
	v_lshlrev_b32_e32 v82, 16, v51
	v_and_b32_e32 v83, 0xffff0000, v51
	v_lshlrev_b32_e32 v136, 16, v52
	v_and_b32_e32 v137, 0xffff0000, v52
	v_lshlrev_b32_e32 v138, 16, v53
	v_and_b32_e32 v139, 0xffff0000, v53
	v_mul_f32_e32 v74, 0xbfb8aa3b, v70
	v_add_f32_e32 v78, v48, v78
	v_pk_mul_f32 v[80:81], v[80:81], v[136:137]
	v_pk_mul_f32 v[82:83], v[82:83], v[138:139]
	v_exp_f32_e32 v74, v74
	v_add_f32_e32 v78, v49, v78
	v_mul_f32_e32 v75, 0xbfb8aa3b, v71
	v_mul_f32_e32 v76, 0xbfb8aa3b, v72
	v_mul_f32_e32 v77, 0xbfb8aa3b, v73
	v_pk_mul_f32 v[80:81], v[104:105], v[80:81]
	v_add_f32_dpp v78, v78, v78 quad_perm:[1,0,3,2] row_mask:0xf bank_mask:0xf bound_ctrl:1
	v_exp_f32_e32 v75, v75
	v_exp_f32_e32 v76, v76
	v_exp_f32_e32 v77, v77
	v_pk_mul_f32 v[82:83], v[106:107], v[82:83]
	v_add_f32_e32 v116, v80, v81
	v_add_f32_dpp v78, v78, v78 quad_perm:[2,3,0,1] row_mask:0xf bank_mask:0xf bound_ctrl:1
	v_add_f32_e32 v116, v82, v116
	v_add_f32_e32 v116, v83, v116
	v_add_f32_dpp v78, v78, v78 row_half_mirror row_mask:0xf bank_mask:0xf bound_ctrl:1
	v_add_f32_e32 v74, 1.0, v74
	v_add_f32_e32 v75, 1.0, v75
	v_add_f32_dpp v116, v116, v116 quad_perm:[1,0,3,2] row_mask:0xf bank_mask:0xf bound_ctrl:1
	v_add_f32_dpp v78, v78, v78 row_mirror row_mask:0xf bank_mask:0xf bound_ctrl:1
	v_rcp_f32_e32 v74, v74
	v_add_f32_e32 v76, 1.0, v76
	v_add_f32_e32 v77, 1.0, v77
	v_fmamk_f32 v119, v78, 0xbc800000, v47
	v_fmamk_f32 v118, v78, 0xbc800000, v46
	v_fmamk_f32 v121, v78, 0xbc800000, v49
	v_fmamk_f32 v120, v78, 0xbc800000, v48
	v_pk_mul_f32 v[122:123], v[118:119], v[118:119]
	v_rcp_f32_e32 v75, v75
	v_rcp_f32_e32 v76, v76
	v_rcp_f32_e32 v77, v77
	v_pk_mul_f32 v[124:125], v[120:121], v[120:121]
	v_add_f32_e32 v126, v122, v123
	v_add_f32_e32 v126, v124, v126
	v_add_f32_e32 v126, v125, v126
	v_add_f32_dpp v116, v116, v116 quad_perm:[2,3,0,1] row_mask:0xf bank_mask:0xf bound_ctrl:1
	v_lshlrev_b32_e32 v128, 16, v54
	v_and_b32_e32 v129, 0xffff0000, v54
	v_add_f32_dpp v126, v126, v126 quad_perm:[1,0,3,2] row_mask:0xf bank_mask:0xf bound_ctrl:1
	v_lshlrev_b32_e32 v130, 16, v55
	v_and_b32_e32 v131, 0xffff0000, v55
	v_add_f32_dpp v126, v126, v126 quad_perm:[2,3,0,1] row_mask:0xf bank_mask:0xf bound_ctrl:1
	v_add_f32_dpp v116, v116, v116 row_half_mirror row_mask:0xf bank_mask:0xf bound_ctrl:1
	v_mul_f32_e32 v70, v74, v70
	v_add_f32_dpp v126, v126, v126 row_half_mirror row_mask:0xf bank_mask:0xf bound_ctrl:1
	v_mul_f32_e32 v71, v75, v71
	v_mul_f32_e32 v72, v76, v72
	v_add_f32_dpp v126, v126, v126 row_mirror row_mask:0xf bank_mask:0xf bound_ctrl:1
	v_add_f32_dpp v116, v116, v116 row_mirror row_mask:0xf bank_mask:0xf bound_ctrl:1
	v_mul_f32_e32 v73, v77, v73
	v_fmamk_f32 v126, v126, 0x3c800000, v195
	v_mul_f32_e32 v127, 0x4b800000, v126
	v_cmp_gt_f32_e32 vcc, s98, v126
	s_nop 1
	v_cndmask_b32_e32 v126, v126, v127, vcc
	v_rsq_f32_e32 v126, v126
	s_nop 0
	v_mul_f32_e32 v127, 0x45800000, v126
	v_cndmask_b32_e32 v140, v126, v127, vcc
	v_pk_mul_f32 v[138:139], v[120:121], v[140:141] op_sel_hi:[1,0]
	v_pk_mul_f32 v[136:137], v[118:119], v[140:141] op_sel_hi:[1,0]
	v_pk_fma_f32 v[134:135], v[110:111], v[138:139], v[114:115]
	v_pk_fma_f32 v[132:133], v[108:109], v[136:137], v[112:113]
	v_pk_fma_f32 v[134:135], v[116:117], v[130:131], v[134:135] op_sel_hi:[0,1,1]
	v_pk_fma_f32 v[132:133], v[116:117], v[128:129], v[132:133] op_sel_hi:[0,1,1]
	v_mul_f32_e32 v132, v70, v132
	v_mul_f32_e32 v133, v71, v133
	v_mul_f32_e32 v134, v72, v134
	v_mul_f32_e32 v135, v73, v135
	v_cvt_pk_bf16_f32 v142, v132, v133
	v_cvt_pk_bf16_f32 v143, v134, v135
	global_store_dwordx2 v101, v[142:143], s[62:63]
	s_add_u32 s62, s62, 0x200000
	s_addc_u32 s63, s63, 0
	global_load_dwordx2 v[44:45], v101, s[60:61] offset:3328
	global_load_dwordx4 v[46:49], v100, s[40:41]
	global_load_dwordx2 v[50:51], v101, s[54:55]
	global_load_dwordx2 v[52:53], v101, s[56:57]
	global_load_dwordx2 v[54:55], v101, s[58:59]
	s_add_u32 s60, s60, 0x6c0000
	s_addc_u32 s61, s61, 0
	s_add_u32 s40, s40, 0x200000
	s_addc_u32 s41, s41, 0
	s_add_u32 s54, s54, 0x100000
	s_addc_u32 s55, s55, 0
	s_add_u32 s56, s56, 0x100000
	s_addc_u32 s57, s57, 0
	s_add_u32 s58, s58, 0x100000
	s_addc_u32 s59, s59, 0
	s_waitcnt vmcnt(18)
	v_lshlrev_b32_e32 v70, 16, v56
	v_and_b32_e32 v71, 0xffff0000, v56
	v_lshlrev_b32_e32 v72, 16, v57
	v_and_b32_e32 v73, 0xffff0000, v57
	v_add_f32_e32 v78, v58, v59
	v_lshlrev_b32_e32 v80, 16, v62
	v_and_b32_e32 v81, 0xffff0000, v62
	v_lshlrev_b32_e32 v82, 16, v63
	v_and_b32_e32 v83, 0xffff0000, v63
	v_lshlrev_b32_e32 v136, 16, v64
	v_and_b32_e32 v137, 0xffff0000, v64
	v_lshlrev_b32_e32 v138, 16, v65
	v_and_b32_e32 v139, 0xffff0000, v65
	v_mul_f32_e32 v74, 0xbfb8aa3b, v70
	v_add_f32_e32 v78, v60, v78
	v_pk_mul_f32 v[80:81], v[80:81], v[136:137]
	v_pk_mul_f32 v[82:83], v[82:83], v[138:139]
	v_exp_f32_e32 v74, v74
	v_add_f32_e32 v78, v61, v78
	v_mul_f32_e32 v75, 0xbfb8aa3b, v71
	v_mul_f32_e32 v76, 0xbfb8aa3b, v72
	v_mul_f32_e32 v77, 0xbfb8aa3b, v73
	v_pk_mul_f32 v[80:81], v[104:105], v[80:81]
	v_add_f32_dpp v78, v78, v78 quad_perm:[1,0,3,2] row_mask:0xf bank_mask:0xf bound_ctrl:1
	v_exp_f32_e32 v75, v75
	v_exp_f32_e32 v76, v76
	v_exp_f32_e32 v77, v77
	v_pk_mul_f32 v[82:83], v[106:107], v[82:83]
	v_add_f32_e32 v116, v80, v81
	v_add_f32_dpp v78, v78, v78 quad_perm:[2,3,0,1] row_mask:0xf bank_mask:0xf bound_ctrl:1
	v_add_f32_e32 v116, v82, v116
	v_add_f32_e32 v116, v83, v116
	v_add_f32_dpp v78, v78, v78 row_half_mirror row_mask:0xf bank_mask:0xf bound_ctrl:1
	v_add_f32_e32 v74, 1.0, v74
	v_add_f32_e32 v75, 1.0, v75
	v_add_f32_dpp v116, v116, v116 quad_perm:[1,0,3,2] row_mask:0xf bank_mask:0xf bound_ctrl:1
	v_add_f32_dpp v78, v78, v78 row_mirror row_mask:0xf bank_mask:0xf bound_ctrl:1
	v_rcp_f32_e32 v74, v74
	v_add_f32_e32 v76, 1.0, v76
	v_add_f32_e32 v77, 1.0, v77
	v_fmamk_f32 v119, v78, 0xbc800000, v59
	v_fmamk_f32 v118, v78, 0xbc800000, v58
	v_fmamk_f32 v121, v78, 0xbc800000, v61
	v_fmamk_f32 v120, v78, 0xbc800000, v60
	v_pk_mul_f32 v[122:123], v[118:119], v[118:119]
	v_rcp_f32_e32 v75, v75
	v_rcp_f32_e32 v76, v76
	v_rcp_f32_e32 v77, v77
	v_pk_mul_f32 v[124:125], v[120:121], v[120:121]
	v_add_f32_e32 v126, v122, v123
	v_add_f32_e32 v126, v124, v126
	v_add_f32_e32 v126, v125, v126
	v_add_f32_dpp v116, v116, v116 quad_perm:[2,3,0,1] row_mask:0xf bank_mask:0xf bound_ctrl:1
	v_lshlrev_b32_e32 v128, 16, v66
	v_and_b32_e32 v129, 0xffff0000, v66
	v_add_f32_dpp v126, v126, v126 quad_perm:[1,0,3,2] row_mask:0xf bank_mask:0xf bound_ctrl:1
	v_lshlrev_b32_e32 v130, 16, v67
	v_and_b32_e32 v131, 0xffff0000, v67
	v_add_f32_dpp v126, v126, v126 quad_perm:[2,3,0,1] row_mask:0xf bank_mask:0xf bound_ctrl:1
	v_add_f32_dpp v116, v116, v116 row_half_mirror row_mask:0xf bank_mask:0xf bound_ctrl:1
	v_mul_f32_e32 v70, v74, v70
	v_add_f32_dpp v126, v126, v126 row_half_mirror row_mask:0xf bank_mask:0xf bound_ctrl:1
	v_mul_f32_e32 v71, v75, v71
	v_mul_f32_e32 v72, v76, v72
	v_add_f32_dpp v126, v126, v126 row_mirror row_mask:0xf bank_mask:0xf bound_ctrl:1
	v_add_f32_dpp v116, v116, v116 row_mirror row_mask:0xf bank_mask:0xf bound_ctrl:1
	v_mul_f32_e32 v73, v77, v73
	v_fmamk_f32 v126, v126, 0x3c800000, v195
	v_mul_f32_e32 v127, 0x4b800000, v126
	v_cmp_gt_f32_e32 vcc, s98, v126
	s_nop 1
	v_cndmask_b32_e32 v126, v126, v127, vcc
	v_rsq_f32_e32 v126, v126
	s_nop 0
	v_mul_f32_e32 v127, 0x45800000, v126
	v_cndmask_b32_e32 v140, v126, v127, vcc
	v_pk_mul_f32 v[138:139], v[120:121], v[140:141] op_sel_hi:[1,0]
	v_pk_mul_f32 v[136:137], v[118:119], v[140:141] op_sel_hi:[1,0]
	v_pk_fma_f32 v[134:135], v[110:111], v[138:139], v[114:115]
	v_pk_fma_f32 v[132:133], v[108:109], v[136:137], v[112:113]
	v_pk_fma_f32 v[134:135], v[116:117], v[130:131], v[134:135] op_sel_hi:[0,1,1]
	v_pk_fma_f32 v[132:133], v[116:117], v[128:129], v[132:133] op_sel_hi:[0,1,1]
	v_mul_f32_e32 v132, v70, v132
	v_mul_f32_e32 v133, v71, v133
	v_mul_f32_e32 v134, v72, v134
	v_mul_f32_e32 v135, v73, v135
	v_cvt_pk_bf16_f32 v142, v132, v133
	v_cvt_pk_bf16_f32 v143, v134, v135
	global_store_dwordx2 v101, v[142:143], s[62:63]
	s_add_u32 s62, s62, 0x200000
	s_addc_u32 s63, s63, 0
	global_load_dwordx2 v[56:57], v101, s[60:61] offset:3328
	global_load_dwordx4 v[58:61], v100, s[40:41]
	global_load_dwordx2 v[62:63], v101, s[54:55]
	global_load_dwordx2 v[64:65], v101, s[56:57]
	global_load_dwordx2 v[66:67], v101, s[58:59]
	s_add_u32 s60, s60, 0x6c0000
	s_addc_u32 s61, s61, 0
	s_add_u32 s40, s40, 0x200000
	s_addc_u32 s41, s41, 0
	s_add_u32 s54, s54, 0x100000
	s_addc_u32 s55, s55, 0
	s_add_u32 s56, s56, 0x100000
	s_addc_u32 s57, s57, 0
	s_add_u32 s58, s58, 0x100000
	s_addc_u32 s59, s59, 0
	s_waitcnt vmcnt(18)
	v_lshlrev_b32_e32 v70, 16, v20
	v_and_b32_e32 v71, 0xffff0000, v20
	v_lshlrev_b32_e32 v72, 16, v21
	v_and_b32_e32 v73, 0xffff0000, v21
	v_add_f32_e32 v78, v22, v23
	v_lshlrev_b32_e32 v80, 16, v26
	v_and_b32_e32 v81, 0xffff0000, v26
	v_lshlrev_b32_e32 v82, 16, v27
	v_and_b32_e32 v83, 0xffff0000, v27
	v_lshlrev_b32_e32 v136, 16, v28
	v_and_b32_e32 v137, 0xffff0000, v28
	v_lshlrev_b32_e32 v138, 16, v29
	v_and_b32_e32 v139, 0xffff0000, v29
	v_mul_f32_e32 v74, 0xbfb8aa3b, v70
	v_add_f32_e32 v78, v24, v78
	v_pk_mul_f32 v[80:81], v[80:81], v[136:137]
	v_pk_mul_f32 v[82:83], v[82:83], v[138:139]
	v_exp_f32_e32 v74, v74
	v_add_f32_e32 v78, v25, v78
	v_mul_f32_e32 v75, 0xbfb8aa3b, v71
	v_mul_f32_e32 v76, 0xbfb8aa3b, v72
	v_mul_f32_e32 v77, 0xbfb8aa3b, v73
	v_pk_mul_f32 v[80:81], v[104:105], v[80:81]
	v_add_f32_dpp v78, v78, v78 quad_perm:[1,0,3,2] row_mask:0xf bank_mask:0xf bound_ctrl:1
	v_exp_f32_e32 v75, v75
	v_exp_f32_e32 v76, v76
	v_exp_f32_e32 v77, v77
	v_pk_mul_f32 v[82:83], v[106:107], v[82:83]
	v_add_f32_e32 v116, v80, v81
	v_add_f32_dpp v78, v78, v78 quad_perm:[2,3,0,1] row_mask:0xf bank_mask:0xf bound_ctrl:1
	v_add_f32_e32 v116, v82, v116
	v_add_f32_e32 v116, v83, v116
	v_add_f32_dpp v78, v78, v78 row_half_mirror row_mask:0xf bank_mask:0xf bound_ctrl:1
	v_add_f32_e32 v74, 1.0, v74
	v_add_f32_e32 v75, 1.0, v75
	v_add_f32_dpp v116, v116, v116 quad_perm:[1,0,3,2] row_mask:0xf bank_mask:0xf bound_ctrl:1
	v_add_f32_dpp v78, v78, v78 row_mirror row_mask:0xf bank_mask:0xf bound_ctrl:1
	v_rcp_f32_e32 v74, v74
	v_add_f32_e32 v76, 1.0, v76
	v_add_f32_e32 v77, 1.0, v77
	v_fmamk_f32 v119, v78, 0xbc800000, v23
	v_fmamk_f32 v118, v78, 0xbc800000, v22
	v_fmamk_f32 v121, v78, 0xbc800000, v25
	v_fmamk_f32 v120, v78, 0xbc800000, v24
	v_pk_mul_f32 v[122:123], v[118:119], v[118:119]
	v_rcp_f32_e32 v75, v75
	v_rcp_f32_e32 v76, v76
	v_rcp_f32_e32 v77, v77
	v_pk_mul_f32 v[124:125], v[120:121], v[120:121]
	v_add_f32_e32 v126, v122, v123
	v_add_f32_e32 v126, v124, v126
	v_add_f32_e32 v126, v125, v126
	v_add_f32_dpp v116, v116, v116 quad_perm:[2,3,0,1] row_mask:0xf bank_mask:0xf bound_ctrl:1
	v_lshlrev_b32_e32 v128, 16, v30
	v_and_b32_e32 v129, 0xffff0000, v30
	v_add_f32_dpp v126, v126, v126 quad_perm:[1,0,3,2] row_mask:0xf bank_mask:0xf bound_ctrl:1
	v_lshlrev_b32_e32 v130, 16, v31
	v_and_b32_e32 v131, 0xffff0000, v31
	v_add_f32_dpp v126, v126, v126 quad_perm:[2,3,0,1] row_mask:0xf bank_mask:0xf bound_ctrl:1
	v_add_f32_dpp v116, v116, v116 row_half_mirror row_mask:0xf bank_mask:0xf bound_ctrl:1
	v_mul_f32_e32 v70, v74, v70
	v_add_f32_dpp v126, v126, v126 row_half_mirror row_mask:0xf bank_mask:0xf bound_ctrl:1
	v_mul_f32_e32 v71, v75, v71
	v_mul_f32_e32 v72, v76, v72
	v_add_f32_dpp v126, v126, v126 row_mirror row_mask:0xf bank_mask:0xf bound_ctrl:1
	v_add_f32_dpp v116, v116, v116 row_mirror row_mask:0xf bank_mask:0xf bound_ctrl:1
	v_mul_f32_e32 v73, v77, v73
	v_fmamk_f32 v126, v126, 0x3c800000, v195
	v_mul_f32_e32 v127, 0x4b800000, v126
	v_cmp_gt_f32_e32 vcc, s98, v126
	s_nop 1
	v_cndmask_b32_e32 v126, v126, v127, vcc
	v_rsq_f32_e32 v126, v126
	s_nop 0
	v_mul_f32_e32 v127, 0x45800000, v126
	v_cndmask_b32_e32 v140, v126, v127, vcc
	v_pk_mul_f32 v[138:139], v[120:121], v[140:141] op_sel_hi:[1,0]
	v_pk_mul_f32 v[136:137], v[118:119], v[140:141] op_sel_hi:[1,0]
	v_pk_fma_f32 v[134:135], v[110:111], v[138:139], v[114:115]
	v_pk_fma_f32 v[132:133], v[108:109], v[136:137], v[112:113]
	v_pk_fma_f32 v[134:135], v[116:117], v[130:131], v[134:135] op_sel_hi:[0,1,1]
	v_pk_fma_f32 v[132:133], v[116:117], v[128:129], v[132:133] op_sel_hi:[0,1,1]
	v_mul_f32_e32 v132, v70, v132
	v_mul_f32_e32 v133, v71, v133
	v_mul_f32_e32 v134, v72, v134
	v_mul_f32_e32 v135, v73, v135
	v_cvt_pk_bf16_f32 v142, v132, v133
	v_cvt_pk_bf16_f32 v143, v134, v135
	global_store_dwordx2 v101, v[142:143], s[62:63]
	s_add_u32 s62, s62, 0x200000
	s_addc_u32 s63, s63, 0
	global_load_dwordx2 v[20:21], v101, s[60:61] offset:3328
	global_load_dwordx4 v[22:25], v100, s[40:41]
	global_load_dwordx2 v[26:27], v101, s[54:55]
	global_load_dwordx2 v[28:29], v101, s[56:57]
	global_load_dwordx2 v[30:31], v101, s[58:59]
	s_add_u32 s60, s60, 0x6c0000
	s_addc_u32 s61, s61, 0
	s_add_u32 s40, s40, 0x200000
	s_addc_u32 s41, s41, 0
	s_add_u32 s54, s54, 0x100000
	s_addc_u32 s55, s55, 0
	s_add_u32 s56, s56, 0x100000
	s_addc_u32 s57, s57, 0
	s_add_u32 s58, s58, 0x100000
	s_addc_u32 s59, s59, 0
	s_waitcnt vmcnt(18)
	v_lshlrev_b32_e32 v70, 16, v32
	v_and_b32_e32 v71, 0xffff0000, v32
	v_lshlrev_b32_e32 v72, 16, v33
	v_and_b32_e32 v73, 0xffff0000, v33
	v_add_f32_e32 v78, v34, v35
	v_lshlrev_b32_e32 v80, 16, v38
	v_and_b32_e32 v81, 0xffff0000, v38
	v_lshlrev_b32_e32 v82, 16, v39
	v_and_b32_e32 v83, 0xffff0000, v39
	v_lshlrev_b32_e32 v136, 16, v40
	v_and_b32_e32 v137, 0xffff0000, v40
	v_lshlrev_b32_e32 v138, 16, v41
	v_and_b32_e32 v139, 0xffff0000, v41
	v_mul_f32_e32 v74, 0xbfb8aa3b, v70
	v_add_f32_e32 v78, v36, v78
	v_pk_mul_f32 v[80:81], v[80:81], v[136:137]
	v_pk_mul_f32 v[82:83], v[82:83], v[138:139]
	v_exp_f32_e32 v74, v74
	v_add_f32_e32 v78, v37, v78
	v_mul_f32_e32 v75, 0xbfb8aa3b, v71
	v_mul_f32_e32 v76, 0xbfb8aa3b, v72
	v_mul_f32_e32 v77, 0xbfb8aa3b, v73
	v_pk_mul_f32 v[80:81], v[104:105], v[80:81]
	v_add_f32_dpp v78, v78, v78 quad_perm:[1,0,3,2] row_mask:0xf bank_mask:0xf bound_ctrl:1
	v_exp_f32_e32 v75, v75
	v_exp_f32_e32 v76, v76
	v_exp_f32_e32 v77, v77
	v_pk_mul_f32 v[82:83], v[106:107], v[82:83]
	v_add_f32_e32 v116, v80, v81
	v_add_f32_dpp v78, v78, v78 quad_perm:[2,3,0,1] row_mask:0xf bank_mask:0xf bound_ctrl:1
	v_add_f32_e32 v116, v82, v116
	v_add_f32_e32 v116, v83, v116
	v_add_f32_dpp v78, v78, v78 row_half_mirror row_mask:0xf bank_mask:0xf bound_ctrl:1
	v_add_f32_e32 v74, 1.0, v74
	v_add_f32_e32 v75, 1.0, v75
	v_add_f32_dpp v116, v116, v116 quad_perm:[1,0,3,2] row_mask:0xf bank_mask:0xf bound_ctrl:1
	v_add_f32_dpp v78, v78, v78 row_mirror row_mask:0xf bank_mask:0xf bound_ctrl:1
	v_rcp_f32_e32 v74, v74
	v_add_f32_e32 v76, 1.0, v76
	v_add_f32_e32 v77, 1.0, v77
	v_fmamk_f32 v119, v78, 0xbc800000, v35
	v_fmamk_f32 v118, v78, 0xbc800000, v34
	v_fmamk_f32 v121, v78, 0xbc800000, v37
	v_fmamk_f32 v120, v78, 0xbc800000, v36
	v_pk_mul_f32 v[122:123], v[118:119], v[118:119]
	v_rcp_f32_e32 v75, v75
	v_rcp_f32_e32 v76, v76
	v_rcp_f32_e32 v77, v77
	v_pk_mul_f32 v[124:125], v[120:121], v[120:121]
	v_add_f32_e32 v126, v122, v123
	v_add_f32_e32 v126, v124, v126
	v_add_f32_e32 v126, v125, v126
	v_add_f32_dpp v116, v116, v116 quad_perm:[2,3,0,1] row_mask:0xf bank_mask:0xf bound_ctrl:1
	v_lshlrev_b32_e32 v128, 16, v42
	v_and_b32_e32 v129, 0xffff0000, v42
	v_add_f32_dpp v126, v126, v126 quad_perm:[1,0,3,2] row_mask:0xf bank_mask:0xf bound_ctrl:1
	v_lshlrev_b32_e32 v130, 16, v43
	v_and_b32_e32 v131, 0xffff0000, v43
	v_add_f32_dpp v126, v126, v126 quad_perm:[2,3,0,1] row_mask:0xf bank_mask:0xf bound_ctrl:1
	v_add_f32_dpp v116, v116, v116 row_half_mirror row_mask:0xf bank_mask:0xf bound_ctrl:1
	v_mul_f32_e32 v70, v74, v70
	v_add_f32_dpp v126, v126, v126 row_half_mirror row_mask:0xf bank_mask:0xf bound_ctrl:1
	v_mul_f32_e32 v71, v75, v71
	v_mul_f32_e32 v72, v76, v72
	v_add_f32_dpp v126, v126, v126 row_mirror row_mask:0xf bank_mask:0xf bound_ctrl:1
	v_add_f32_dpp v116, v116, v116 row_mirror row_mask:0xf bank_mask:0xf bound_ctrl:1
	v_mul_f32_e32 v73, v77, v73
	v_fmamk_f32 v126, v126, 0x3c800000, v195
	v_mul_f32_e32 v127, 0x4b800000, v126
	v_cmp_gt_f32_e32 vcc, s98, v126
	s_nop 1
	v_cndmask_b32_e32 v126, v126, v127, vcc
	v_rsq_f32_e32 v126, v126
	s_nop 0
	v_mul_f32_e32 v127, 0x45800000, v126
	v_cndmask_b32_e32 v140, v126, v127, vcc
	v_pk_mul_f32 v[138:139], v[120:121], v[140:141] op_sel_hi:[1,0]
	v_pk_mul_f32 v[136:137], v[118:119], v[140:141] op_sel_hi:[1,0]
	v_pk_fma_f32 v[134:135], v[110:111], v[138:139], v[114:115]
	v_pk_fma_f32 v[132:133], v[108:109], v[136:137], v[112:113]
	v_pk_fma_f32 v[134:135], v[116:117], v[130:131], v[134:135] op_sel_hi:[0,1,1]
	v_pk_fma_f32 v[132:133], v[116:117], v[128:129], v[132:133] op_sel_hi:[0,1,1]
	v_mul_f32_e32 v132, v70, v132
	v_mul_f32_e32 v133, v71, v133
	v_mul_f32_e32 v134, v72, v134
	v_mul_f32_e32 v135, v73, v135
	v_cvt_pk_bf16_f32 v142, v132, v133
	v_cvt_pk_bf16_f32 v143, v134, v135
	global_store_dwordx2 v101, v[142:143], s[62:63]
	s_add_u32 s62, s62, 0x200000
	s_addc_u32 s63, s63, 0
	global_load_dwordx2 v[32:33], v101, s[60:61] offset:3328
	global_load_dwordx4 v[34:37], v100, s[40:41]
	global_load_dwordx2 v[38:39], v101, s[54:55]
	global_load_dwordx2 v[40:41], v101, s[56:57]
	global_load_dwordx2 v[42:43], v101, s[58:59]
	s_add_u32 s60, s60, 0x6c0000
	s_addc_u32 s61, s61, 0
	s_add_u32 s40, s40, 0x200000
	s_addc_u32 s41, s41, 0
	s_add_u32 s54, s54, 0x100000
	s_addc_u32 s55, s55, 0
	s_add_u32 s56, s56, 0x100000
	s_addc_u32 s57, s57, 0
	s_add_u32 s58, s58, 0x100000
	s_addc_u32 s59, s59, 0
	s_waitcnt vmcnt(18)
	v_lshlrev_b32_e32 v70, 16, v44
	v_and_b32_e32 v71, 0xffff0000, v44
	v_lshlrev_b32_e32 v72, 16, v45
	v_and_b32_e32 v73, 0xffff0000, v45
	v_add_f32_e32 v78, v46, v47
	v_lshlrev_b32_e32 v80, 16, v50
	v_and_b32_e32 v81, 0xffff0000, v50
	v_lshlrev_b32_e32 v82, 16, v51
	v_and_b32_e32 v83, 0xffff0000, v51
	v_lshlrev_b32_e32 v136, 16, v52
	v_and_b32_e32 v137, 0xffff0000, v52
	v_lshlrev_b32_e32 v138, 16, v53
	v_and_b32_e32 v139, 0xffff0000, v53
	v_mul_f32_e32 v74, 0xbfb8aa3b, v70
	v_add_f32_e32 v78, v48, v78
	v_pk_mul_f32 v[80:81], v[80:81], v[136:137]
	v_pk_mul_f32 v[82:83], v[82:83], v[138:139]
	v_exp_f32_e32 v74, v74
	v_add_f32_e32 v78, v49, v78
	v_mul_f32_e32 v75, 0xbfb8aa3b, v71
	v_mul_f32_e32 v76, 0xbfb8aa3b, v72
	v_mul_f32_e32 v77, 0xbfb8aa3b, v73
	v_pk_mul_f32 v[80:81], v[104:105], v[80:81]
	v_add_f32_dpp v78, v78, v78 quad_perm:[1,0,3,2] row_mask:0xf bank_mask:0xf bound_ctrl:1
	v_exp_f32_e32 v75, v75
	v_exp_f32_e32 v76, v76
	v_exp_f32_e32 v77, v77
	v_pk_mul_f32 v[82:83], v[106:107], v[82:83]
	v_add_f32_e32 v116, v80, v81
	v_add_f32_dpp v78, v78, v78 quad_perm:[2,3,0,1] row_mask:0xf bank_mask:0xf bound_ctrl:1
	v_add_f32_e32 v116, v82, v116
	v_add_f32_e32 v116, v83, v116
	v_add_f32_dpp v78, v78, v78 row_half_mirror row_mask:0xf bank_mask:0xf bound_ctrl:1
	v_add_f32_e32 v74, 1.0, v74
	v_add_f32_e32 v75, 1.0, v75
	v_add_f32_dpp v116, v116, v116 quad_perm:[1,0,3,2] row_mask:0xf bank_mask:0xf bound_ctrl:1
	v_add_f32_dpp v78, v78, v78 row_mirror row_mask:0xf bank_mask:0xf bound_ctrl:1
	v_rcp_f32_e32 v74, v74
	v_add_f32_e32 v76, 1.0, v76
	v_add_f32_e32 v77, 1.0, v77
	v_fmamk_f32 v119, v78, 0xbc800000, v47
	v_fmamk_f32 v118, v78, 0xbc800000, v46
	v_fmamk_f32 v121, v78, 0xbc800000, v49
	v_fmamk_f32 v120, v78, 0xbc800000, v48
	v_pk_mul_f32 v[122:123], v[118:119], v[118:119]
	v_rcp_f32_e32 v75, v75
	v_rcp_f32_e32 v76, v76
	v_rcp_f32_e32 v77, v77
	v_pk_mul_f32 v[124:125], v[120:121], v[120:121]
	v_add_f32_e32 v126, v122, v123
	v_add_f32_e32 v126, v124, v126
	v_add_f32_e32 v126, v125, v126
	v_add_f32_dpp v116, v116, v116 quad_perm:[2,3,0,1] row_mask:0xf bank_mask:0xf bound_ctrl:1
	v_lshlrev_b32_e32 v128, 16, v54
	v_and_b32_e32 v129, 0xffff0000, v54
	v_add_f32_dpp v126, v126, v126 quad_perm:[1,0,3,2] row_mask:0xf bank_mask:0xf bound_ctrl:1
	v_lshlrev_b32_e32 v130, 16, v55
	v_and_b32_e32 v131, 0xffff0000, v55
	v_add_f32_dpp v126, v126, v126 quad_perm:[2,3,0,1] row_mask:0xf bank_mask:0xf bound_ctrl:1
	v_add_f32_dpp v116, v116, v116 row_half_mirror row_mask:0xf bank_mask:0xf bound_ctrl:1
	v_mul_f32_e32 v70, v74, v70
	v_add_f32_dpp v126, v126, v126 row_half_mirror row_mask:0xf bank_mask:0xf bound_ctrl:1
	v_mul_f32_e32 v71, v75, v71
	v_mul_f32_e32 v72, v76, v72
	v_add_f32_dpp v126, v126, v126 row_mirror row_mask:0xf bank_mask:0xf bound_ctrl:1
	v_add_f32_dpp v116, v116, v116 row_mirror row_mask:0xf bank_mask:0xf bound_ctrl:1
	v_mul_f32_e32 v73, v77, v73
	v_fmamk_f32 v126, v126, 0x3c800000, v195
	v_mul_f32_e32 v127, 0x4b800000, v126
	v_cmp_gt_f32_e32 vcc, s98, v126
	s_nop 1
	v_cndmask_b32_e32 v126, v126, v127, vcc
	v_rsq_f32_e32 v126, v126
	s_nop 0
	v_mul_f32_e32 v127, 0x45800000, v126
	v_cndmask_b32_e32 v140, v126, v127, vcc
	v_pk_mul_f32 v[138:139], v[120:121], v[140:141] op_sel_hi:[1,0]
	v_pk_mul_f32 v[136:137], v[118:119], v[140:141] op_sel_hi:[1,0]
	v_pk_fma_f32 v[134:135], v[110:111], v[138:139], v[114:115]
	v_pk_fma_f32 v[132:133], v[108:109], v[136:137], v[112:113]
	v_pk_fma_f32 v[134:135], v[116:117], v[130:131], v[134:135] op_sel_hi:[0,1,1]
	v_pk_fma_f32 v[132:133], v[116:117], v[128:129], v[132:133] op_sel_hi:[0,1,1]
	v_mul_f32_e32 v132, v70, v132
	v_mul_f32_e32 v133, v71, v133
	v_mul_f32_e32 v134, v72, v134
	v_mul_f32_e32 v135, v73, v135
	v_cvt_pk_bf16_f32 v142, v132, v133
	v_cvt_pk_bf16_f32 v143, v134, v135
	global_store_dwordx2 v101, v[142:143], s[62:63]
	s_add_u32 s62, s62, 0x200000
	s_addc_u32 s63, s63, 0
	global_load_dwordx2 v[44:45], v101, s[60:61] offset:3328
	global_load_dwordx4 v[46:49], v100, s[40:41]
	global_load_dwordx2 v[50:51], v101, s[54:55]
	global_load_dwordx2 v[52:53], v101, s[56:57]
	global_load_dwordx2 v[54:55], v101, s[58:59]
	s_add_u32 s60, s60, 0x6c0000
	s_addc_u32 s61, s61, 0
	s_add_u32 s40, s40, 0x200000
	s_addc_u32 s41, s41, 0
	s_add_u32 s54, s54, 0x100000
	s_addc_u32 s55, s55, 0
	s_add_u32 s56, s56, 0x100000
	s_addc_u32 s57, s57, 0
	s_add_u32 s58, s58, 0x100000
	s_addc_u32 s59, s59, 0
	s_waitcnt vmcnt(18)
	v_lshlrev_b32_e32 v70, 16, v56
	v_and_b32_e32 v71, 0xffff0000, v56
	v_lshlrev_b32_e32 v72, 16, v57
	v_and_b32_e32 v73, 0xffff0000, v57
	v_add_f32_e32 v78, v58, v59
	v_lshlrev_b32_e32 v80, 16, v62
	v_and_b32_e32 v81, 0xffff0000, v62
	v_lshlrev_b32_e32 v82, 16, v63
	v_and_b32_e32 v83, 0xffff0000, v63
	v_lshlrev_b32_e32 v136, 16, v64
	v_and_b32_e32 v137, 0xffff0000, v64
	v_lshlrev_b32_e32 v138, 16, v65
	v_and_b32_e32 v139, 0xffff0000, v65
	v_mul_f32_e32 v74, 0xbfb8aa3b, v70
	v_add_f32_e32 v78, v60, v78
	v_pk_mul_f32 v[80:81], v[80:81], v[136:137]
	v_pk_mul_f32 v[82:83], v[82:83], v[138:139]
	v_exp_f32_e32 v74, v74
	v_add_f32_e32 v78, v61, v78
	v_mul_f32_e32 v75, 0xbfb8aa3b, v71
	v_mul_f32_e32 v76, 0xbfb8aa3b, v72
	v_mul_f32_e32 v77, 0xbfb8aa3b, v73
	v_pk_mul_f32 v[80:81], v[104:105], v[80:81]
	v_add_f32_dpp v78, v78, v78 quad_perm:[1,0,3,2] row_mask:0xf bank_mask:0xf bound_ctrl:1
	v_exp_f32_e32 v75, v75
	v_exp_f32_e32 v76, v76
	v_exp_f32_e32 v77, v77
	v_pk_mul_f32 v[82:83], v[106:107], v[82:83]
	v_add_f32_e32 v116, v80, v81
	v_add_f32_dpp v78, v78, v78 quad_perm:[2,3,0,1] row_mask:0xf bank_mask:0xf bound_ctrl:1
	v_add_f32_e32 v116, v82, v116
	v_add_f32_e32 v116, v83, v116
	v_add_f32_dpp v78, v78, v78 row_half_mirror row_mask:0xf bank_mask:0xf bound_ctrl:1
	v_add_f32_e32 v74, 1.0, v74
	v_add_f32_e32 v75, 1.0, v75
	v_add_f32_dpp v116, v116, v116 quad_perm:[1,0,3,2] row_mask:0xf bank_mask:0xf bound_ctrl:1
	v_add_f32_dpp v78, v78, v78 row_mirror row_mask:0xf bank_mask:0xf bound_ctrl:1
	v_rcp_f32_e32 v74, v74
	v_add_f32_e32 v76, 1.0, v76
	v_add_f32_e32 v77, 1.0, v77
	v_fmamk_f32 v119, v78, 0xbc800000, v59
	v_fmamk_f32 v118, v78, 0xbc800000, v58
	v_fmamk_f32 v121, v78, 0xbc800000, v61
	v_fmamk_f32 v120, v78, 0xbc800000, v60
	v_pk_mul_f32 v[122:123], v[118:119], v[118:119]
	v_rcp_f32_e32 v75, v75
	v_rcp_f32_e32 v76, v76
	v_rcp_f32_e32 v77, v77
	v_pk_mul_f32 v[124:125], v[120:121], v[120:121]
	v_add_f32_e32 v126, v122, v123
	v_add_f32_e32 v126, v124, v126
	v_add_f32_e32 v126, v125, v126
	v_add_f32_dpp v116, v116, v116 quad_perm:[2,3,0,1] row_mask:0xf bank_mask:0xf bound_ctrl:1
	v_lshlrev_b32_e32 v128, 16, v66
	v_and_b32_e32 v129, 0xffff0000, v66
	v_add_f32_dpp v126, v126, v126 quad_perm:[1,0,3,2] row_mask:0xf bank_mask:0xf bound_ctrl:1
	v_lshlrev_b32_e32 v130, 16, v67
	v_and_b32_e32 v131, 0xffff0000, v67
	v_add_f32_dpp v126, v126, v126 quad_perm:[2,3,0,1] row_mask:0xf bank_mask:0xf bound_ctrl:1
	v_add_f32_dpp v116, v116, v116 row_half_mirror row_mask:0xf bank_mask:0xf bound_ctrl:1
	v_mul_f32_e32 v70, v74, v70
	v_add_f32_dpp v126, v126, v126 row_half_mirror row_mask:0xf bank_mask:0xf bound_ctrl:1
	v_mul_f32_e32 v71, v75, v71
	v_mul_f32_e32 v72, v76, v72
	v_add_f32_dpp v126, v126, v126 row_mirror row_mask:0xf bank_mask:0xf bound_ctrl:1
	v_add_f32_dpp v116, v116, v116 row_mirror row_mask:0xf bank_mask:0xf bound_ctrl:1
	v_mul_f32_e32 v73, v77, v73
	v_fmamk_f32 v126, v126, 0x3c800000, v195
	v_mul_f32_e32 v127, 0x4b800000, v126
	v_cmp_gt_f32_e32 vcc, s98, v126
	s_nop 1
	v_cndmask_b32_e32 v126, v126, v127, vcc
	v_rsq_f32_e32 v126, v126
	s_nop 0
	v_mul_f32_e32 v127, 0x45800000, v126
	v_cndmask_b32_e32 v140, v126, v127, vcc
	v_pk_mul_f32 v[138:139], v[120:121], v[140:141] op_sel_hi:[1,0]
	v_pk_mul_f32 v[136:137], v[118:119], v[140:141] op_sel_hi:[1,0]
	v_pk_fma_f32 v[134:135], v[110:111], v[138:139], v[114:115]
	v_pk_fma_f32 v[132:133], v[108:109], v[136:137], v[112:113]
	v_pk_fma_f32 v[134:135], v[116:117], v[130:131], v[134:135] op_sel_hi:[0,1,1]
	v_pk_fma_f32 v[132:133], v[116:117], v[128:129], v[132:133] op_sel_hi:[0,1,1]
	v_mul_f32_e32 v132, v70, v132
	v_mul_f32_e32 v133, v71, v133
	v_mul_f32_e32 v134, v72, v134
	v_mul_f32_e32 v135, v73, v135
	v_cvt_pk_bf16_f32 v142, v132, v133
	v_cvt_pk_bf16_f32 v143, v134, v135
	global_store_dwordx2 v101, v[142:143], s[62:63]
	s_add_u32 s62, s62, 0x200000
	s_addc_u32 s63, s63, 0
	global_load_dwordx2 v[56:57], v101, s[60:61] offset:3328
	global_load_dwordx4 v[58:61], v100, s[40:41]
	global_load_dwordx2 v[62:63], v101, s[54:55]
	global_load_dwordx2 v[64:65], v101, s[56:57]
	global_load_dwordx2 v[66:67], v101, s[58:59]
	s_add_u32 s60, s60, 0x6c0000
	s_addc_u32 s61, s61, 0
	s_add_u32 s40, s40, 0x200000
	s_addc_u32 s41, s41, 0
	s_add_u32 s54, s54, 0x100000
	s_addc_u32 s55, s55, 0
	s_add_u32 s56, s56, 0x100000
	s_addc_u32 s57, s57, 0
	s_add_u32 s58, s58, 0x100000
	s_addc_u32 s59, s59, 0
	s_waitcnt vmcnt(18)
	v_lshlrev_b32_e32 v70, 16, v20
	v_and_b32_e32 v71, 0xffff0000, v20
	v_lshlrev_b32_e32 v72, 16, v21
	v_and_b32_e32 v73, 0xffff0000, v21
	v_add_f32_e32 v78, v22, v23
	v_lshlrev_b32_e32 v80, 16, v26
	v_and_b32_e32 v81, 0xffff0000, v26
	v_lshlrev_b32_e32 v82, 16, v27
	v_and_b32_e32 v83, 0xffff0000, v27
	v_lshlrev_b32_e32 v136, 16, v28
	v_and_b32_e32 v137, 0xffff0000, v28
	v_lshlrev_b32_e32 v138, 16, v29
	v_and_b32_e32 v139, 0xffff0000, v29
	v_mul_f32_e32 v74, 0xbfb8aa3b, v70
	v_add_f32_e32 v78, v24, v78
	v_pk_mul_f32 v[80:81], v[80:81], v[136:137]
	v_pk_mul_f32 v[82:83], v[82:83], v[138:139]
	v_exp_f32_e32 v74, v74
	v_add_f32_e32 v78, v25, v78
	v_mul_f32_e32 v75, 0xbfb8aa3b, v71
	v_mul_f32_e32 v76, 0xbfb8aa3b, v72
	v_mul_f32_e32 v77, 0xbfb8aa3b, v73
	v_pk_mul_f32 v[80:81], v[104:105], v[80:81]
	v_add_f32_dpp v78, v78, v78 quad_perm:[1,0,3,2] row_mask:0xf bank_mask:0xf bound_ctrl:1
	v_exp_f32_e32 v75, v75
	v_exp_f32_e32 v76, v76
	v_exp_f32_e32 v77, v77
	v_pk_mul_f32 v[82:83], v[106:107], v[82:83]
	v_add_f32_e32 v116, v80, v81
	v_add_f32_dpp v78, v78, v78 quad_perm:[2,3,0,1] row_mask:0xf bank_mask:0xf bound_ctrl:1
	v_add_f32_e32 v116, v82, v116
	v_add_f32_e32 v116, v83, v116
	v_add_f32_dpp v78, v78, v78 row_half_mirror row_mask:0xf bank_mask:0xf bound_ctrl:1
	v_add_f32_e32 v74, 1.0, v74
	v_add_f32_e32 v75, 1.0, v75
	v_add_f32_dpp v116, v116, v116 quad_perm:[1,0,3,2] row_mask:0xf bank_mask:0xf bound_ctrl:1
	v_add_f32_dpp v78, v78, v78 row_mirror row_mask:0xf bank_mask:0xf bound_ctrl:1
	v_rcp_f32_e32 v74, v74
	v_add_f32_e32 v76, 1.0, v76
	v_add_f32_e32 v77, 1.0, v77
	v_fmamk_f32 v119, v78, 0xbc800000, v23
	v_fmamk_f32 v118, v78, 0xbc800000, v22
	v_fmamk_f32 v121, v78, 0xbc800000, v25
	v_fmamk_f32 v120, v78, 0xbc800000, v24
	v_pk_mul_f32 v[122:123], v[118:119], v[118:119]
	v_rcp_f32_e32 v75, v75
	v_rcp_f32_e32 v76, v76
	v_rcp_f32_e32 v77, v77
	v_pk_mul_f32 v[124:125], v[120:121], v[120:121]
	v_add_f32_e32 v126, v122, v123
	v_add_f32_e32 v126, v124, v126
	v_add_f32_e32 v126, v125, v126
	v_add_f32_dpp v116, v116, v116 quad_perm:[2,3,0,1] row_mask:0xf bank_mask:0xf bound_ctrl:1
	v_lshlrev_b32_e32 v128, 16, v30
	v_and_b32_e32 v129, 0xffff0000, v30
	v_add_f32_dpp v126, v126, v126 quad_perm:[1,0,3,2] row_mask:0xf bank_mask:0xf bound_ctrl:1
	v_lshlrev_b32_e32 v130, 16, v31
	v_and_b32_e32 v131, 0xffff0000, v31
	v_add_f32_dpp v126, v126, v126 quad_perm:[2,3,0,1] row_mask:0xf bank_mask:0xf bound_ctrl:1
	v_add_f32_dpp v116, v116, v116 row_half_mirror row_mask:0xf bank_mask:0xf bound_ctrl:1
	v_mul_f32_e32 v70, v74, v70
	v_add_f32_dpp v126, v126, v126 row_half_mirror row_mask:0xf bank_mask:0xf bound_ctrl:1
	v_mul_f32_e32 v71, v75, v71
	v_mul_f32_e32 v72, v76, v72
	v_add_f32_dpp v126, v126, v126 row_mirror row_mask:0xf bank_mask:0xf bound_ctrl:1
	v_add_f32_dpp v116, v116, v116 row_mirror row_mask:0xf bank_mask:0xf bound_ctrl:1
	v_mul_f32_e32 v73, v77, v73
	v_fmamk_f32 v126, v126, 0x3c800000, v195
	v_mul_f32_e32 v127, 0x4b800000, v126
	v_cmp_gt_f32_e32 vcc, s98, v126
	s_nop 1
	v_cndmask_b32_e32 v126, v126, v127, vcc
	v_rsq_f32_e32 v126, v126
	s_nop 0
	v_mul_f32_e32 v127, 0x45800000, v126
	v_cndmask_b32_e32 v140, v126, v127, vcc
	v_pk_mul_f32 v[138:139], v[120:121], v[140:141] op_sel_hi:[1,0]
	v_pk_mul_f32 v[136:137], v[118:119], v[140:141] op_sel_hi:[1,0]
	v_pk_fma_f32 v[134:135], v[110:111], v[138:139], v[114:115]
	v_pk_fma_f32 v[132:133], v[108:109], v[136:137], v[112:113]
	v_pk_fma_f32 v[134:135], v[116:117], v[130:131], v[134:135] op_sel_hi:[0,1,1]
	v_pk_fma_f32 v[132:133], v[116:117], v[128:129], v[132:133] op_sel_hi:[0,1,1]
	v_mul_f32_e32 v132, v70, v132
	v_mul_f32_e32 v133, v71, v133
	v_mul_f32_e32 v134, v72, v134
	v_mul_f32_e32 v135, v73, v135
	v_cvt_pk_bf16_f32 v142, v132, v133
	v_cvt_pk_bf16_f32 v143, v134, v135
	global_store_dwordx2 v101, v[142:143], s[62:63]
	s_add_u32 s62, s62, 0x200000
	s_addc_u32 s63, s63, 0
	global_load_dwordx2 v[20:21], v101, s[60:61] offset:3328
	global_load_dwordx4 v[22:25], v100, s[40:41]
	global_load_dwordx2 v[26:27], v101, s[54:55]
	global_load_dwordx2 v[28:29], v101, s[56:57]
	global_load_dwordx2 v[30:31], v101, s[58:59]
	s_add_u32 s60, s60, 0x6c0000
	s_addc_u32 s61, s61, 0
	s_add_u32 s40, s40, 0x200000
	s_addc_u32 s41, s41, 0
	s_add_u32 s54, s54, 0x100000
	s_addc_u32 s55, s55, 0
	s_add_u32 s56, s56, 0x100000
	s_addc_u32 s57, s57, 0
	s_add_u32 s58, s58, 0x100000
	s_addc_u32 s59, s59, 0
	s_waitcnt vmcnt(18)
	v_lshlrev_b32_e32 v70, 16, v32
	v_and_b32_e32 v71, 0xffff0000, v32
	v_lshlrev_b32_e32 v72, 16, v33
	v_and_b32_e32 v73, 0xffff0000, v33
	v_add_f32_e32 v78, v34, v35
	v_lshlrev_b32_e32 v80, 16, v38
	v_and_b32_e32 v81, 0xffff0000, v38
	v_lshlrev_b32_e32 v82, 16, v39
	v_and_b32_e32 v83, 0xffff0000, v39
	v_lshlrev_b32_e32 v136, 16, v40
	v_and_b32_e32 v137, 0xffff0000, v40
	v_lshlrev_b32_e32 v138, 16, v41
	v_and_b32_e32 v139, 0xffff0000, v41
	v_mul_f32_e32 v74, 0xbfb8aa3b, v70
	v_add_f32_e32 v78, v36, v78
	v_pk_mul_f32 v[80:81], v[80:81], v[136:137]
	v_pk_mul_f32 v[82:83], v[82:83], v[138:139]
	v_exp_f32_e32 v74, v74
	v_add_f32_e32 v78, v37, v78
	v_mul_f32_e32 v75, 0xbfb8aa3b, v71
	v_mul_f32_e32 v76, 0xbfb8aa3b, v72
	v_mul_f32_e32 v77, 0xbfb8aa3b, v73
	v_pk_mul_f32 v[80:81], v[104:105], v[80:81]
	v_add_f32_dpp v78, v78, v78 quad_perm:[1,0,3,2] row_mask:0xf bank_mask:0xf bound_ctrl:1
	v_exp_f32_e32 v75, v75
	v_exp_f32_e32 v76, v76
	v_exp_f32_e32 v77, v77
	v_pk_mul_f32 v[82:83], v[106:107], v[82:83]
	v_add_f32_e32 v116, v80, v81
	v_add_f32_dpp v78, v78, v78 quad_perm:[2,3,0,1] row_mask:0xf bank_mask:0xf bound_ctrl:1
	v_add_f32_e32 v116, v82, v116
	v_add_f32_e32 v116, v83, v116
	v_add_f32_dpp v78, v78, v78 row_half_mirror row_mask:0xf bank_mask:0xf bound_ctrl:1
	v_add_f32_e32 v74, 1.0, v74
	v_add_f32_e32 v75, 1.0, v75
	v_add_f32_dpp v116, v116, v116 quad_perm:[1,0,3,2] row_mask:0xf bank_mask:0xf bound_ctrl:1
	v_add_f32_dpp v78, v78, v78 row_mirror row_mask:0xf bank_mask:0xf bound_ctrl:1
	v_rcp_f32_e32 v74, v74
	v_add_f32_e32 v76, 1.0, v76
	v_add_f32_e32 v77, 1.0, v77
	v_fmamk_f32 v119, v78, 0xbc800000, v35
	v_fmamk_f32 v118, v78, 0xbc800000, v34
	v_fmamk_f32 v121, v78, 0xbc800000, v37
	v_fmamk_f32 v120, v78, 0xbc800000, v36
	v_pk_mul_f32 v[122:123], v[118:119], v[118:119]
	v_rcp_f32_e32 v75, v75
	v_rcp_f32_e32 v76, v76
	v_rcp_f32_e32 v77, v77
	v_pk_mul_f32 v[124:125], v[120:121], v[120:121]
	v_add_f32_e32 v126, v122, v123
	v_add_f32_e32 v126, v124, v126
	v_add_f32_e32 v126, v125, v126
	v_add_f32_dpp v116, v116, v116 quad_perm:[2,3,0,1] row_mask:0xf bank_mask:0xf bound_ctrl:1
	v_lshlrev_b32_e32 v128, 16, v42
	v_and_b32_e32 v129, 0xffff0000, v42
	v_add_f32_dpp v126, v126, v126 quad_perm:[1,0,3,2] row_mask:0xf bank_mask:0xf bound_ctrl:1
	v_lshlrev_b32_e32 v130, 16, v43
	v_and_b32_e32 v131, 0xffff0000, v43
	v_add_f32_dpp v126, v126, v126 quad_perm:[2,3,0,1] row_mask:0xf bank_mask:0xf bound_ctrl:1
	v_add_f32_dpp v116, v116, v116 row_half_mirror row_mask:0xf bank_mask:0xf bound_ctrl:1
	v_mul_f32_e32 v70, v74, v70
	v_add_f32_dpp v126, v126, v126 row_half_mirror row_mask:0xf bank_mask:0xf bound_ctrl:1
	v_mul_f32_e32 v71, v75, v71
	v_mul_f32_e32 v72, v76, v72
	v_add_f32_dpp v126, v126, v126 row_mirror row_mask:0xf bank_mask:0xf bound_ctrl:1
	v_add_f32_dpp v116, v116, v116 row_mirror row_mask:0xf bank_mask:0xf bound_ctrl:1
	v_mul_f32_e32 v73, v77, v73
	v_fmamk_f32 v126, v126, 0x3c800000, v195
	v_mul_f32_e32 v127, 0x4b800000, v126
	v_cmp_gt_f32_e32 vcc, s98, v126
	s_nop 1
	v_cndmask_b32_e32 v126, v126, v127, vcc
	v_rsq_f32_e32 v126, v126
	s_nop 0
	v_mul_f32_e32 v127, 0x45800000, v126
	v_cndmask_b32_e32 v140, v126, v127, vcc
	v_pk_mul_f32 v[138:139], v[120:121], v[140:141] op_sel_hi:[1,0]
	v_pk_mul_f32 v[136:137], v[118:119], v[140:141] op_sel_hi:[1,0]
	v_pk_fma_f32 v[134:135], v[110:111], v[138:139], v[114:115]
	v_pk_fma_f32 v[132:133], v[108:109], v[136:137], v[112:113]
	v_pk_fma_f32 v[134:135], v[116:117], v[130:131], v[134:135] op_sel_hi:[0,1,1]
	v_pk_fma_f32 v[132:133], v[116:117], v[128:129], v[132:133] op_sel_hi:[0,1,1]
	v_mul_f32_e32 v132, v70, v132
	v_mul_f32_e32 v133, v71, v133
	v_mul_f32_e32 v134, v72, v134
	v_mul_f32_e32 v135, v73, v135
	v_cvt_pk_bf16_f32 v142, v132, v133
	v_cvt_pk_bf16_f32 v143, v134, v135
	global_store_dwordx2 v101, v[142:143], s[62:63]
	s_add_u32 s62, s62, 0x200000
	s_addc_u32 s63, s63, 0
	global_load_dwordx2 v[32:33], v101, s[60:61] offset:3328
	global_load_dwordx4 v[34:37], v100, s[40:41]
	global_load_dwordx2 v[38:39], v101, s[54:55]
	global_load_dwordx2 v[40:41], v101, s[56:57]
	global_load_dwordx2 v[42:43], v101, s[58:59]
	s_add_u32 s60, s60, 0x6c0000
	s_addc_u32 s61, s61, 0
	s_add_u32 s40, s40, 0x200000
	s_addc_u32 s41, s41, 0
	s_add_u32 s54, s54, 0x100000
	s_addc_u32 s55, s55, 0
	s_add_u32 s56, s56, 0x100000
	s_addc_u32 s57, s57, 0
	s_add_u32 s58, s58, 0x100000
	s_addc_u32 s59, s59, 0
	s_waitcnt vmcnt(18)
	v_lshlrev_b32_e32 v70, 16, v44
	v_and_b32_e32 v71, 0xffff0000, v44
	v_lshlrev_b32_e32 v72, 16, v45
	v_and_b32_e32 v73, 0xffff0000, v45
	v_add_f32_e32 v78, v46, v47
	v_lshlrev_b32_e32 v80, 16, v50
	v_and_b32_e32 v81, 0xffff0000, v50
	v_lshlrev_b32_e32 v82, 16, v51
	v_and_b32_e32 v83, 0xffff0000, v51
	v_lshlrev_b32_e32 v136, 16, v52
	v_and_b32_e32 v137, 0xffff0000, v52
	v_lshlrev_b32_e32 v138, 16, v53
	v_and_b32_e32 v139, 0xffff0000, v53
	v_mul_f32_e32 v74, 0xbfb8aa3b, v70
	v_add_f32_e32 v78, v48, v78
	v_pk_mul_f32 v[80:81], v[80:81], v[136:137]
	v_pk_mul_f32 v[82:83], v[82:83], v[138:139]
	v_exp_f32_e32 v74, v74
	v_add_f32_e32 v78, v49, v78
	v_mul_f32_e32 v75, 0xbfb8aa3b, v71
	v_mul_f32_e32 v76, 0xbfb8aa3b, v72
	v_mul_f32_e32 v77, 0xbfb8aa3b, v73
	v_pk_mul_f32 v[80:81], v[104:105], v[80:81]
	v_add_f32_dpp v78, v78, v78 quad_perm:[1,0,3,2] row_mask:0xf bank_mask:0xf bound_ctrl:1
	v_exp_f32_e32 v75, v75
	v_exp_f32_e32 v76, v76
	v_exp_f32_e32 v77, v77
	v_pk_mul_f32 v[82:83], v[106:107], v[82:83]
	v_add_f32_e32 v116, v80, v81
	v_add_f32_dpp v78, v78, v78 quad_perm:[2,3,0,1] row_mask:0xf bank_mask:0xf bound_ctrl:1
	v_add_f32_e32 v116, v82, v116
	v_add_f32_e32 v116, v83, v116
	v_add_f32_dpp v78, v78, v78 row_half_mirror row_mask:0xf bank_mask:0xf bound_ctrl:1
	v_add_f32_e32 v74, 1.0, v74
	v_add_f32_e32 v75, 1.0, v75
	v_add_f32_dpp v116, v116, v116 quad_perm:[1,0,3,2] row_mask:0xf bank_mask:0xf bound_ctrl:1
	v_add_f32_dpp v78, v78, v78 row_mirror row_mask:0xf bank_mask:0xf bound_ctrl:1
	v_rcp_f32_e32 v74, v74
	v_add_f32_e32 v76, 1.0, v76
	v_add_f32_e32 v77, 1.0, v77
	v_fmamk_f32 v119, v78, 0xbc800000, v47
	v_fmamk_f32 v118, v78, 0xbc800000, v46
	v_fmamk_f32 v121, v78, 0xbc800000, v49
	v_fmamk_f32 v120, v78, 0xbc800000, v48
	v_pk_mul_f32 v[122:123], v[118:119], v[118:119]
	v_rcp_f32_e32 v75, v75
	v_rcp_f32_e32 v76, v76
	v_rcp_f32_e32 v77, v77
	v_pk_mul_f32 v[124:125], v[120:121], v[120:121]
	v_add_f32_e32 v126, v122, v123
	v_add_f32_e32 v126, v124, v126
	v_add_f32_e32 v126, v125, v126
	v_add_f32_dpp v116, v116, v116 quad_perm:[2,3,0,1] row_mask:0xf bank_mask:0xf bound_ctrl:1
	v_lshlrev_b32_e32 v128, 16, v54
	v_and_b32_e32 v129, 0xffff0000, v54
	v_add_f32_dpp v126, v126, v126 quad_perm:[1,0,3,2] row_mask:0xf bank_mask:0xf bound_ctrl:1
	v_lshlrev_b32_e32 v130, 16, v55
	v_and_b32_e32 v131, 0xffff0000, v55
	v_add_f32_dpp v126, v126, v126 quad_perm:[2,3,0,1] row_mask:0xf bank_mask:0xf bound_ctrl:1
	v_add_f32_dpp v116, v116, v116 row_half_mirror row_mask:0xf bank_mask:0xf bound_ctrl:1
	v_mul_f32_e32 v70, v74, v70
	v_add_f32_dpp v126, v126, v126 row_half_mirror row_mask:0xf bank_mask:0xf bound_ctrl:1
	v_mul_f32_e32 v71, v75, v71
	v_mul_f32_e32 v72, v76, v72
	v_add_f32_dpp v126, v126, v126 row_mirror row_mask:0xf bank_mask:0xf bound_ctrl:1
	v_add_f32_dpp v116, v116, v116 row_mirror row_mask:0xf bank_mask:0xf bound_ctrl:1
	v_mul_f32_e32 v73, v77, v73
	v_fmamk_f32 v126, v126, 0x3c800000, v195
	v_mul_f32_e32 v127, 0x4b800000, v126
	v_cmp_gt_f32_e32 vcc, s98, v126
	s_nop 1
	v_cndmask_b32_e32 v126, v126, v127, vcc
	v_rsq_f32_e32 v126, v126
	s_nop 0
	v_mul_f32_e32 v127, 0x45800000, v126
	v_cndmask_b32_e32 v140, v126, v127, vcc
	v_pk_mul_f32 v[138:139], v[120:121], v[140:141] op_sel_hi:[1,0]
	v_pk_mul_f32 v[136:137], v[118:119], v[140:141] op_sel_hi:[1,0]
	v_pk_fma_f32 v[134:135], v[110:111], v[138:139], v[114:115]
	v_pk_fma_f32 v[132:133], v[108:109], v[136:137], v[112:113]
	v_pk_fma_f32 v[134:135], v[116:117], v[130:131], v[134:135] op_sel_hi:[0,1,1]
	v_pk_fma_f32 v[132:133], v[116:117], v[128:129], v[132:133] op_sel_hi:[0,1,1]
	v_mul_f32_e32 v132, v70, v132
	v_mul_f32_e32 v133, v71, v133
	v_mul_f32_e32 v134, v72, v134
	v_mul_f32_e32 v135, v73, v135
	v_cvt_pk_bf16_f32 v142, v132, v133
	v_cvt_pk_bf16_f32 v143, v134, v135
	global_store_dwordx2 v101, v[142:143], s[62:63]
	s_add_u32 s62, s62, 0x200000
	s_addc_u32 s63, s63, 0
	global_load_dwordx2 v[44:45], v101, s[60:61] offset:3328
	global_load_dwordx4 v[46:49], v100, s[40:41]
	global_load_dwordx2 v[50:51], v101, s[54:55]
	global_load_dwordx2 v[52:53], v101, s[56:57]
	global_load_dwordx2 v[54:55], v101, s[58:59]
	s_add_u32 s60, s60, 0x6c0000
	s_addc_u32 s61, s61, 0
	s_add_u32 s40, s40, 0x200000
	s_addc_u32 s41, s41, 0
	s_add_u32 s54, s54, 0x100000
	s_addc_u32 s55, s55, 0
	s_add_u32 s56, s56, 0x100000
	s_addc_u32 s57, s57, 0
	s_add_u32 s58, s58, 0x100000
	s_addc_u32 s59, s59, 0
	s_waitcnt vmcnt(18)
	v_lshlrev_b32_e32 v70, 16, v56
	v_and_b32_e32 v71, 0xffff0000, v56
	v_lshlrev_b32_e32 v72, 16, v57
	v_and_b32_e32 v73, 0xffff0000, v57
	v_add_f32_e32 v78, v58, v59
	v_lshlrev_b32_e32 v80, 16, v62
	v_and_b32_e32 v81, 0xffff0000, v62
	v_lshlrev_b32_e32 v82, 16, v63
	v_and_b32_e32 v83, 0xffff0000, v63
	v_lshlrev_b32_e32 v136, 16, v64
	v_and_b32_e32 v137, 0xffff0000, v64
	v_lshlrev_b32_e32 v138, 16, v65
	v_and_b32_e32 v139, 0xffff0000, v65
	v_mul_f32_e32 v74, 0xbfb8aa3b, v70
	v_add_f32_e32 v78, v60, v78
	v_pk_mul_f32 v[80:81], v[80:81], v[136:137]
	v_pk_mul_f32 v[82:83], v[82:83], v[138:139]
	v_exp_f32_e32 v74, v74
	v_add_f32_e32 v78, v61, v78
	v_mul_f32_e32 v75, 0xbfb8aa3b, v71
	v_mul_f32_e32 v76, 0xbfb8aa3b, v72
	v_mul_f32_e32 v77, 0xbfb8aa3b, v73
	v_pk_mul_f32 v[80:81], v[104:105], v[80:81]
	v_add_f32_dpp v78, v78, v78 quad_perm:[1,0,3,2] row_mask:0xf bank_mask:0xf bound_ctrl:1
	v_exp_f32_e32 v75, v75
	v_exp_f32_e32 v76, v76
	v_exp_f32_e32 v77, v77
	v_pk_mul_f32 v[82:83], v[106:107], v[82:83]
	v_add_f32_e32 v116, v80, v81
	v_add_f32_dpp v78, v78, v78 quad_perm:[2,3,0,1] row_mask:0xf bank_mask:0xf bound_ctrl:1
	v_add_f32_e32 v116, v82, v116
	v_add_f32_e32 v116, v83, v116
	v_add_f32_dpp v78, v78, v78 row_half_mirror row_mask:0xf bank_mask:0xf bound_ctrl:1
	v_add_f32_e32 v74, 1.0, v74
	v_add_f32_e32 v75, 1.0, v75
	v_add_f32_dpp v116, v116, v116 quad_perm:[1,0,3,2] row_mask:0xf bank_mask:0xf bound_ctrl:1
	v_add_f32_dpp v78, v78, v78 row_mirror row_mask:0xf bank_mask:0xf bound_ctrl:1
	v_rcp_f32_e32 v74, v74
	v_add_f32_e32 v76, 1.0, v76
	v_add_f32_e32 v77, 1.0, v77
	v_fmamk_f32 v119, v78, 0xbc800000, v59
	v_fmamk_f32 v118, v78, 0xbc800000, v58
	v_fmamk_f32 v121, v78, 0xbc800000, v61
	v_fmamk_f32 v120, v78, 0xbc800000, v60
	v_pk_mul_f32 v[122:123], v[118:119], v[118:119]
	v_rcp_f32_e32 v75, v75
	v_rcp_f32_e32 v76, v76
	v_rcp_f32_e32 v77, v77
	v_pk_mul_f32 v[124:125], v[120:121], v[120:121]
	v_add_f32_e32 v126, v122, v123
	v_add_f32_e32 v126, v124, v126
	v_add_f32_e32 v126, v125, v126
	v_add_f32_dpp v116, v116, v116 quad_perm:[2,3,0,1] row_mask:0xf bank_mask:0xf bound_ctrl:1
	v_lshlrev_b32_e32 v128, 16, v66
	v_and_b32_e32 v129, 0xffff0000, v66
	v_add_f32_dpp v126, v126, v126 quad_perm:[1,0,3,2] row_mask:0xf bank_mask:0xf bound_ctrl:1
	v_lshlrev_b32_e32 v130, 16, v67
	v_and_b32_e32 v131, 0xffff0000, v67
	v_add_f32_dpp v126, v126, v126 quad_perm:[2,3,0,1] row_mask:0xf bank_mask:0xf bound_ctrl:1
	v_add_f32_dpp v116, v116, v116 row_half_mirror row_mask:0xf bank_mask:0xf bound_ctrl:1
	v_mul_f32_e32 v70, v74, v70
	v_add_f32_dpp v126, v126, v126 row_half_mirror row_mask:0xf bank_mask:0xf bound_ctrl:1
	v_mul_f32_e32 v71, v75, v71
	v_mul_f32_e32 v72, v76, v72
	v_add_f32_dpp v126, v126, v126 row_mirror row_mask:0xf bank_mask:0xf bound_ctrl:1
	v_add_f32_dpp v116, v116, v116 row_mirror row_mask:0xf bank_mask:0xf bound_ctrl:1
	v_mul_f32_e32 v73, v77, v73
	v_fmamk_f32 v126, v126, 0x3c800000, v195
	v_mul_f32_e32 v127, 0x4b800000, v126
	v_cmp_gt_f32_e32 vcc, s98, v126
	s_nop 1
	v_cndmask_b32_e32 v126, v126, v127, vcc
	v_rsq_f32_e32 v126, v126
	s_nop 0
	v_mul_f32_e32 v127, 0x45800000, v126
	v_cndmask_b32_e32 v140, v126, v127, vcc
	v_pk_mul_f32 v[138:139], v[120:121], v[140:141] op_sel_hi:[1,0]
	v_pk_mul_f32 v[136:137], v[118:119], v[140:141] op_sel_hi:[1,0]
	v_pk_fma_f32 v[134:135], v[110:111], v[138:139], v[114:115]
	v_pk_fma_f32 v[132:133], v[108:109], v[136:137], v[112:113]
	v_pk_fma_f32 v[134:135], v[116:117], v[130:131], v[134:135] op_sel_hi:[0,1,1]
	v_pk_fma_f32 v[132:133], v[116:117], v[128:129], v[132:133] op_sel_hi:[0,1,1]
	v_mul_f32_e32 v132, v70, v132
	v_mul_f32_e32 v133, v71, v133
	v_mul_f32_e32 v134, v72, v134
	v_mul_f32_e32 v135, v73, v135
	v_cvt_pk_bf16_f32 v142, v132, v133
	v_cvt_pk_bf16_f32 v143, v134, v135
	global_store_dwordx2 v101, v[142:143], s[62:63]
	s_add_u32 s62, s62, 0x200000
	s_addc_u32 s63, s63, 0
	global_load_dwordx2 v[56:57], v101, s[60:61] offset:3328
	global_load_dwordx4 v[58:61], v100, s[40:41]
	global_load_dwordx2 v[62:63], v101, s[54:55]
	global_load_dwordx2 v[64:65], v101, s[56:57]
	global_load_dwordx2 v[66:67], v101, s[58:59]
	s_add_u32 s60, s60, 0x6c0000
	s_addc_u32 s61, s61, 0
	s_add_u32 s40, s40, 0x200000
	s_addc_u32 s41, s41, 0
	s_add_u32 s54, s54, 0x100000
	s_addc_u32 s55, s55, 0
	s_add_u32 s56, s56, 0x100000
	s_addc_u32 s57, s57, 0
	s_add_u32 s58, s58, 0x100000
	s_addc_u32 s59, s59, 0
	s_waitcnt vmcnt(18)
	v_lshlrev_b32_e32 v70, 16, v20
	v_and_b32_e32 v71, 0xffff0000, v20
	v_lshlrev_b32_e32 v72, 16, v21
	v_and_b32_e32 v73, 0xffff0000, v21
	v_add_f32_e32 v78, v22, v23
	v_lshlrev_b32_e32 v80, 16, v26
	v_and_b32_e32 v81, 0xffff0000, v26
	v_lshlrev_b32_e32 v82, 16, v27
	v_and_b32_e32 v83, 0xffff0000, v27
	v_lshlrev_b32_e32 v136, 16, v28
	v_and_b32_e32 v137, 0xffff0000, v28
	v_lshlrev_b32_e32 v138, 16, v29
	v_and_b32_e32 v139, 0xffff0000, v29
	v_mul_f32_e32 v74, 0xbfb8aa3b, v70
	v_add_f32_e32 v78, v24, v78
	v_pk_mul_f32 v[80:81], v[80:81], v[136:137]
	v_pk_mul_f32 v[82:83], v[82:83], v[138:139]
	v_exp_f32_e32 v74, v74
	v_add_f32_e32 v78, v25, v78
	v_mul_f32_e32 v75, 0xbfb8aa3b, v71
	v_mul_f32_e32 v76, 0xbfb8aa3b, v72
	v_mul_f32_e32 v77, 0xbfb8aa3b, v73
	v_pk_mul_f32 v[80:81], v[104:105], v[80:81]
	v_add_f32_dpp v78, v78, v78 quad_perm:[1,0,3,2] row_mask:0xf bank_mask:0xf bound_ctrl:1
	v_exp_f32_e32 v75, v75
	v_exp_f32_e32 v76, v76
	v_exp_f32_e32 v77, v77
	v_pk_mul_f32 v[82:83], v[106:107], v[82:83]
	v_add_f32_e32 v116, v80, v81
	v_add_f32_dpp v78, v78, v78 quad_perm:[2,3,0,1] row_mask:0xf bank_mask:0xf bound_ctrl:1
	v_add_f32_e32 v116, v82, v116
	v_add_f32_e32 v116, v83, v116
	v_add_f32_dpp v78, v78, v78 row_half_mirror row_mask:0xf bank_mask:0xf bound_ctrl:1
	v_add_f32_e32 v74, 1.0, v74
	v_add_f32_e32 v75, 1.0, v75
	v_add_f32_dpp v116, v116, v116 quad_perm:[1,0,3,2] row_mask:0xf bank_mask:0xf bound_ctrl:1
	v_add_f32_dpp v78, v78, v78 row_mirror row_mask:0xf bank_mask:0xf bound_ctrl:1
	v_rcp_f32_e32 v74, v74
	v_add_f32_e32 v76, 1.0, v76
	v_add_f32_e32 v77, 1.0, v77
	v_fmamk_f32 v119, v78, 0xbc800000, v23
	v_fmamk_f32 v118, v78, 0xbc800000, v22
	v_fmamk_f32 v121, v78, 0xbc800000, v25
	v_fmamk_f32 v120, v78, 0xbc800000, v24
	v_pk_mul_f32 v[122:123], v[118:119], v[118:119]
	v_rcp_f32_e32 v75, v75
	v_rcp_f32_e32 v76, v76
	v_rcp_f32_e32 v77, v77
	v_pk_mul_f32 v[124:125], v[120:121], v[120:121]
	v_add_f32_e32 v126, v122, v123
	v_add_f32_e32 v126, v124, v126
	v_add_f32_e32 v126, v125, v126
	v_add_f32_dpp v116, v116, v116 quad_perm:[2,3,0,1] row_mask:0xf bank_mask:0xf bound_ctrl:1
	v_lshlrev_b32_e32 v128, 16, v30
	v_and_b32_e32 v129, 0xffff0000, v30
	v_add_f32_dpp v126, v126, v126 quad_perm:[1,0,3,2] row_mask:0xf bank_mask:0xf bound_ctrl:1
	v_lshlrev_b32_e32 v130, 16, v31
	v_and_b32_e32 v131, 0xffff0000, v31
	v_add_f32_dpp v126, v126, v126 quad_perm:[2,3,0,1] row_mask:0xf bank_mask:0xf bound_ctrl:1
	v_add_f32_dpp v116, v116, v116 row_half_mirror row_mask:0xf bank_mask:0xf bound_ctrl:1
	v_mul_f32_e32 v70, v74, v70
	v_add_f32_dpp v126, v126, v126 row_half_mirror row_mask:0xf bank_mask:0xf bound_ctrl:1
	v_mul_f32_e32 v71, v75, v71
	v_mul_f32_e32 v72, v76, v72
	v_add_f32_dpp v126, v126, v126 row_mirror row_mask:0xf bank_mask:0xf bound_ctrl:1
	v_add_f32_dpp v116, v116, v116 row_mirror row_mask:0xf bank_mask:0xf bound_ctrl:1
	v_mul_f32_e32 v73, v77, v73
	v_fmamk_f32 v126, v126, 0x3c800000, v195
	v_mul_f32_e32 v127, 0x4b800000, v126
	v_cmp_gt_f32_e32 vcc, s98, v126
	s_nop 1
	v_cndmask_b32_e32 v126, v126, v127, vcc
	v_rsq_f32_e32 v126, v126
	s_nop 0
	v_mul_f32_e32 v127, 0x45800000, v126
	v_cndmask_b32_e32 v140, v126, v127, vcc
	v_pk_mul_f32 v[138:139], v[120:121], v[140:141] op_sel_hi:[1,0]
	v_pk_mul_f32 v[136:137], v[118:119], v[140:141] op_sel_hi:[1,0]
	v_pk_fma_f32 v[134:135], v[110:111], v[138:139], v[114:115]
	v_pk_fma_f32 v[132:133], v[108:109], v[136:137], v[112:113]
	v_pk_fma_f32 v[134:135], v[116:117], v[130:131], v[134:135] op_sel_hi:[0,1,1]
	v_pk_fma_f32 v[132:133], v[116:117], v[128:129], v[132:133] op_sel_hi:[0,1,1]
	v_mul_f32_e32 v132, v70, v132
	v_mul_f32_e32 v133, v71, v133
	v_mul_f32_e32 v134, v72, v134
	v_mul_f32_e32 v135, v73, v135
	v_cvt_pk_bf16_f32 v142, v132, v133
	v_cvt_pk_bf16_f32 v143, v134, v135
	global_store_dwordx2 v101, v[142:143], s[62:63]
	s_add_u32 s62, s62, 0x200000
	s_addc_u32 s63, s63, 0
	s_waitcnt vmcnt(13)
	v_lshlrev_b32_e32 v70, 16, v32
	v_and_b32_e32 v71, 0xffff0000, v32
	v_lshlrev_b32_e32 v72, 16, v33
	v_and_b32_e32 v73, 0xffff0000, v33
	v_add_f32_e32 v78, v34, v35
	v_lshlrev_b32_e32 v80, 16, v38
	v_and_b32_e32 v81, 0xffff0000, v38
	v_lshlrev_b32_e32 v82, 16, v39
	v_and_b32_e32 v83, 0xffff0000, v39
	v_lshlrev_b32_e32 v136, 16, v40
	v_and_b32_e32 v137, 0xffff0000, v40
	v_lshlrev_b32_e32 v138, 16, v41
	v_and_b32_e32 v139, 0xffff0000, v41
	v_mul_f32_e32 v74, 0xbfb8aa3b, v70
	v_add_f32_e32 v78, v36, v78
	v_pk_mul_f32 v[80:81], v[80:81], v[136:137]
	v_pk_mul_f32 v[82:83], v[82:83], v[138:139]
	v_exp_f32_e32 v74, v74
	v_add_f32_e32 v78, v37, v78
	v_mul_f32_e32 v75, 0xbfb8aa3b, v71
	v_mul_f32_e32 v76, 0xbfb8aa3b, v72
	v_mul_f32_e32 v77, 0xbfb8aa3b, v73
	v_pk_mul_f32 v[80:81], v[104:105], v[80:81]
	v_add_f32_dpp v78, v78, v78 quad_perm:[1,0,3,2] row_mask:0xf bank_mask:0xf bound_ctrl:1
	v_exp_f32_e32 v75, v75
	v_exp_f32_e32 v76, v76
	v_exp_f32_e32 v77, v77
	v_pk_mul_f32 v[82:83], v[106:107], v[82:83]
	v_add_f32_e32 v116, v80, v81
	v_add_f32_dpp v78, v78, v78 quad_perm:[2,3,0,1] row_mask:0xf bank_mask:0xf bound_ctrl:1
	v_add_f32_e32 v116, v82, v116
	v_add_f32_e32 v116, v83, v116
	v_add_f32_dpp v78, v78, v78 row_half_mirror row_mask:0xf bank_mask:0xf bound_ctrl:1
	v_add_f32_e32 v74, 1.0, v74
	v_add_f32_e32 v75, 1.0, v75
	v_add_f32_dpp v116, v116, v116 quad_perm:[1,0,3,2] row_mask:0xf bank_mask:0xf bound_ctrl:1
	v_add_f32_dpp v78, v78, v78 row_mirror row_mask:0xf bank_mask:0xf bound_ctrl:1
	v_rcp_f32_e32 v74, v74
	v_add_f32_e32 v76, 1.0, v76
	v_add_f32_e32 v77, 1.0, v77
	v_fmamk_f32 v119, v78, 0xbc800000, v35
	v_fmamk_f32 v118, v78, 0xbc800000, v34
	v_fmamk_f32 v121, v78, 0xbc800000, v37
	v_fmamk_f32 v120, v78, 0xbc800000, v36
	v_pk_mul_f32 v[122:123], v[118:119], v[118:119]
	v_rcp_f32_e32 v75, v75
	v_rcp_f32_e32 v76, v76
	v_rcp_f32_e32 v77, v77
	v_pk_mul_f32 v[124:125], v[120:121], v[120:121]
	v_add_f32_e32 v126, v122, v123
	v_add_f32_e32 v126, v124, v126
	v_add_f32_e32 v126, v125, v126
	v_add_f32_dpp v116, v116, v116 quad_perm:[2,3,0,1] row_mask:0xf bank_mask:0xf bound_ctrl:1
	v_lshlrev_b32_e32 v128, 16, v42
	v_and_b32_e32 v129, 0xffff0000, v42
	v_add_f32_dpp v126, v126, v126 quad_perm:[1,0,3,2] row_mask:0xf bank_mask:0xf bound_ctrl:1
	v_lshlrev_b32_e32 v130, 16, v43
	v_and_b32_e32 v131, 0xffff0000, v43
	v_add_f32_dpp v126, v126, v126 quad_perm:[2,3,0,1] row_mask:0xf bank_mask:0xf bound_ctrl:1
	v_add_f32_dpp v116, v116, v116 row_half_mirror row_mask:0xf bank_mask:0xf bound_ctrl:1
	v_mul_f32_e32 v70, v74, v70
	v_add_f32_dpp v126, v126, v126 row_half_mirror row_mask:0xf bank_mask:0xf bound_ctrl:1
	v_mul_f32_e32 v71, v75, v71
	v_mul_f32_e32 v72, v76, v72
	v_add_f32_dpp v126, v126, v126 row_mirror row_mask:0xf bank_mask:0xf bound_ctrl:1
	v_add_f32_dpp v116, v116, v116 row_mirror row_mask:0xf bank_mask:0xf bound_ctrl:1
	v_mul_f32_e32 v73, v77, v73
	v_fmamk_f32 v126, v126, 0x3c800000, v195
	v_mul_f32_e32 v127, 0x4b800000, v126
	v_cmp_gt_f32_e32 vcc, s98, v126
	s_nop 1
	v_cndmask_b32_e32 v126, v126, v127, vcc
	v_rsq_f32_e32 v126, v126
	s_nop 0
	v_mul_f32_e32 v127, 0x45800000, v126
	v_cndmask_b32_e32 v140, v126, v127, vcc
	v_pk_mul_f32 v[138:139], v[120:121], v[140:141] op_sel_hi:[1,0]
	v_pk_mul_f32 v[136:137], v[118:119], v[140:141] op_sel_hi:[1,0]
	v_pk_fma_f32 v[134:135], v[110:111], v[138:139], v[114:115]
	v_pk_fma_f32 v[132:133], v[108:109], v[136:137], v[112:113]
	v_pk_fma_f32 v[134:135], v[116:117], v[130:131], v[134:135] op_sel_hi:[0,1,1]
	v_pk_fma_f32 v[132:133], v[116:117], v[128:129], v[132:133] op_sel_hi:[0,1,1]
	v_mul_f32_e32 v132, v70, v132
	v_mul_f32_e32 v133, v71, v133
	v_mul_f32_e32 v134, v72, v134
	v_mul_f32_e32 v135, v73, v135
	v_cvt_pk_bf16_f32 v142, v132, v133
	v_cvt_pk_bf16_f32 v143, v134, v135
	global_store_dwordx2 v101, v[142:143], s[62:63]
	s_add_u32 s62, s62, 0x200000
	s_addc_u32 s63, s63, 0
	s_waitcnt vmcnt(8)
	v_lshlrev_b32_e32 v70, 16, v44
	v_and_b32_e32 v71, 0xffff0000, v44
	v_lshlrev_b32_e32 v72, 16, v45
	v_and_b32_e32 v73, 0xffff0000, v45
	v_add_f32_e32 v78, v46, v47
	v_lshlrev_b32_e32 v80, 16, v50
	v_and_b32_e32 v81, 0xffff0000, v50
	v_lshlrev_b32_e32 v82, 16, v51
	v_and_b32_e32 v83, 0xffff0000, v51
	v_lshlrev_b32_e32 v136, 16, v52
	v_and_b32_e32 v137, 0xffff0000, v52
	v_lshlrev_b32_e32 v138, 16, v53
	v_and_b32_e32 v139, 0xffff0000, v53
	v_mul_f32_e32 v74, 0xbfb8aa3b, v70
	v_add_f32_e32 v78, v48, v78
	v_pk_mul_f32 v[80:81], v[80:81], v[136:137]
	v_pk_mul_f32 v[82:83], v[82:83], v[138:139]
	v_exp_f32_e32 v74, v74
	v_add_f32_e32 v78, v49, v78
	v_mul_f32_e32 v75, 0xbfb8aa3b, v71
	v_mul_f32_e32 v76, 0xbfb8aa3b, v72
	v_mul_f32_e32 v77, 0xbfb8aa3b, v73
	v_pk_mul_f32 v[80:81], v[104:105], v[80:81]
	v_add_f32_dpp v78, v78, v78 quad_perm:[1,0,3,2] row_mask:0xf bank_mask:0xf bound_ctrl:1
	v_exp_f32_e32 v75, v75
	v_exp_f32_e32 v76, v76
	v_exp_f32_e32 v77, v77
	v_pk_mul_f32 v[82:83], v[106:107], v[82:83]
	v_add_f32_e32 v116, v80, v81
	v_add_f32_dpp v78, v78, v78 quad_perm:[2,3,0,1] row_mask:0xf bank_mask:0xf bound_ctrl:1
	v_add_f32_e32 v116, v82, v116
	v_add_f32_e32 v116, v83, v116
	v_add_f32_dpp v78, v78, v78 row_half_mirror row_mask:0xf bank_mask:0xf bound_ctrl:1
	v_add_f32_e32 v74, 1.0, v74
	v_add_f32_e32 v75, 1.0, v75
	v_add_f32_dpp v116, v116, v116 quad_perm:[1,0,3,2] row_mask:0xf bank_mask:0xf bound_ctrl:1
	v_add_f32_dpp v78, v78, v78 row_mirror row_mask:0xf bank_mask:0xf bound_ctrl:1
	v_rcp_f32_e32 v74, v74
	v_add_f32_e32 v76, 1.0, v76
	v_add_f32_e32 v77, 1.0, v77
	v_fmamk_f32 v119, v78, 0xbc800000, v47
	v_fmamk_f32 v118, v78, 0xbc800000, v46
	v_fmamk_f32 v121, v78, 0xbc800000, v49
	v_fmamk_f32 v120, v78, 0xbc800000, v48
	v_pk_mul_f32 v[122:123], v[118:119], v[118:119]
	v_rcp_f32_e32 v75, v75
	v_rcp_f32_e32 v76, v76
	v_rcp_f32_e32 v77, v77
	v_pk_mul_f32 v[124:125], v[120:121], v[120:121]
	v_add_f32_e32 v126, v122, v123
	v_add_f32_e32 v126, v124, v126
	v_add_f32_e32 v126, v125, v126
	v_add_f32_dpp v116, v116, v116 quad_perm:[2,3,0,1] row_mask:0xf bank_mask:0xf bound_ctrl:1
	v_lshlrev_b32_e32 v128, 16, v54
	v_and_b32_e32 v129, 0xffff0000, v54
	v_add_f32_dpp v126, v126, v126 quad_perm:[1,0,3,2] row_mask:0xf bank_mask:0xf bound_ctrl:1
	v_lshlrev_b32_e32 v130, 16, v55
	v_and_b32_e32 v131, 0xffff0000, v55
	v_add_f32_dpp v126, v126, v126 quad_perm:[2,3,0,1] row_mask:0xf bank_mask:0xf bound_ctrl:1
	v_add_f32_dpp v116, v116, v116 row_half_mirror row_mask:0xf bank_mask:0xf bound_ctrl:1
	v_mul_f32_e32 v70, v74, v70
	v_add_f32_dpp v126, v126, v126 row_half_mirror row_mask:0xf bank_mask:0xf bound_ctrl:1
	v_mul_f32_e32 v71, v75, v71
	v_mul_f32_e32 v72, v76, v72
	v_add_f32_dpp v126, v126, v126 row_mirror row_mask:0xf bank_mask:0xf bound_ctrl:1
	v_add_f32_dpp v116, v116, v116 row_mirror row_mask:0xf bank_mask:0xf bound_ctrl:1
	v_mul_f32_e32 v73, v77, v73
	v_fmamk_f32 v126, v126, 0x3c800000, v195
	v_mul_f32_e32 v127, 0x4b800000, v126
	v_cmp_gt_f32_e32 vcc, s98, v126
	s_nop 1
	v_cndmask_b32_e32 v126, v126, v127, vcc
	v_rsq_f32_e32 v126, v126
	s_nop 0
	v_mul_f32_e32 v127, 0x45800000, v126
	v_cndmask_b32_e32 v140, v126, v127, vcc
	v_pk_mul_f32 v[138:139], v[120:121], v[140:141] op_sel_hi:[1,0]
	v_pk_mul_f32 v[136:137], v[118:119], v[140:141] op_sel_hi:[1,0]
	v_pk_fma_f32 v[134:135], v[110:111], v[138:139], v[114:115]
	v_pk_fma_f32 v[132:133], v[108:109], v[136:137], v[112:113]
	v_pk_fma_f32 v[134:135], v[116:117], v[130:131], v[134:135] op_sel_hi:[0,1,1]
	v_pk_fma_f32 v[132:133], v[116:117], v[128:129], v[132:133] op_sel_hi:[0,1,1]
	v_mul_f32_e32 v132, v70, v132
	v_mul_f32_e32 v133, v71, v133
	v_mul_f32_e32 v134, v72, v134
	v_mul_f32_e32 v135, v73, v135
	v_cvt_pk_bf16_f32 v142, v132, v133
	v_cvt_pk_bf16_f32 v143, v134, v135
	global_store_dwordx2 v101, v[142:143], s[62:63]
	s_add_u32 s62, s62, 0x200000
	s_addc_u32 s63, s63, 0
	s_waitcnt vmcnt(3)
	v_lshlrev_b32_e32 v70, 16, v56
	v_and_b32_e32 v71, 0xffff0000, v56
	v_lshlrev_b32_e32 v72, 16, v57
	v_and_b32_e32 v73, 0xffff0000, v57
	v_add_f32_e32 v78, v58, v59
	v_lshlrev_b32_e32 v80, 16, v62
	v_and_b32_e32 v81, 0xffff0000, v62
	v_lshlrev_b32_e32 v82, 16, v63
	v_and_b32_e32 v83, 0xffff0000, v63
	v_lshlrev_b32_e32 v136, 16, v64
	v_and_b32_e32 v137, 0xffff0000, v64
	v_lshlrev_b32_e32 v138, 16, v65
	v_and_b32_e32 v139, 0xffff0000, v65
	v_mul_f32_e32 v74, 0xbfb8aa3b, v70
	v_add_f32_e32 v78, v60, v78
	v_pk_mul_f32 v[80:81], v[80:81], v[136:137]
	v_pk_mul_f32 v[82:83], v[82:83], v[138:139]
	v_exp_f32_e32 v74, v74
	v_add_f32_e32 v78, v61, v78
	v_mul_f32_e32 v75, 0xbfb8aa3b, v71
	v_mul_f32_e32 v76, 0xbfb8aa3b, v72
	v_mul_f32_e32 v77, 0xbfb8aa3b, v73
	v_pk_mul_f32 v[80:81], v[104:105], v[80:81]
	v_add_f32_dpp v78, v78, v78 quad_perm:[1,0,3,2] row_mask:0xf bank_mask:0xf bound_ctrl:1
	v_exp_f32_e32 v75, v75
	v_exp_f32_e32 v76, v76
	v_exp_f32_e32 v77, v77
	v_pk_mul_f32 v[82:83], v[106:107], v[82:83]
	v_add_f32_e32 v116, v80, v81
	v_add_f32_dpp v78, v78, v78 quad_perm:[2,3,0,1] row_mask:0xf bank_mask:0xf bound_ctrl:1
	v_add_f32_e32 v116, v82, v116
	v_add_f32_e32 v116, v83, v116
	v_add_f32_dpp v78, v78, v78 row_half_mirror row_mask:0xf bank_mask:0xf bound_ctrl:1
	v_add_f32_e32 v74, 1.0, v74
	v_add_f32_e32 v75, 1.0, v75
	v_add_f32_dpp v116, v116, v116 quad_perm:[1,0,3,2] row_mask:0xf bank_mask:0xf bound_ctrl:1
	v_add_f32_dpp v78, v78, v78 row_mirror row_mask:0xf bank_mask:0xf bound_ctrl:1
	v_rcp_f32_e32 v74, v74
	v_add_f32_e32 v76, 1.0, v76
	v_add_f32_e32 v77, 1.0, v77
	v_fmamk_f32 v119, v78, 0xbc800000, v59
	v_fmamk_f32 v118, v78, 0xbc800000, v58
	v_fmamk_f32 v121, v78, 0xbc800000, v61
	v_fmamk_f32 v120, v78, 0xbc800000, v60
	v_pk_mul_f32 v[122:123], v[118:119], v[118:119]
	v_rcp_f32_e32 v75, v75
	v_rcp_f32_e32 v76, v76
	v_rcp_f32_e32 v77, v77
	v_pk_mul_f32 v[124:125], v[120:121], v[120:121]
	v_add_f32_e32 v126, v122, v123
	v_add_f32_e32 v126, v124, v126
	v_add_f32_e32 v126, v125, v126
	v_add_f32_dpp v116, v116, v116 quad_perm:[2,3,0,1] row_mask:0xf bank_mask:0xf bound_ctrl:1
	v_lshlrev_b32_e32 v128, 16, v66
	v_and_b32_e32 v129, 0xffff0000, v66
	v_add_f32_dpp v126, v126, v126 quad_perm:[1,0,3,2] row_mask:0xf bank_mask:0xf bound_ctrl:1
	v_lshlrev_b32_e32 v130, 16, v67
	v_and_b32_e32 v131, 0xffff0000, v67
	v_add_f32_dpp v126, v126, v126 quad_perm:[2,3,0,1] row_mask:0xf bank_mask:0xf bound_ctrl:1
	v_add_f32_dpp v116, v116, v116 row_half_mirror row_mask:0xf bank_mask:0xf bound_ctrl:1
	v_mul_f32_e32 v70, v74, v70
	v_add_f32_dpp v126, v126, v126 row_half_mirror row_mask:0xf bank_mask:0xf bound_ctrl:1
	v_mul_f32_e32 v71, v75, v71
	v_mul_f32_e32 v72, v76, v72
	v_add_f32_dpp v126, v126, v126 row_mirror row_mask:0xf bank_mask:0xf bound_ctrl:1
	v_add_f32_dpp v116, v116, v116 row_mirror row_mask:0xf bank_mask:0xf bound_ctrl:1
	v_mul_f32_e32 v73, v77, v73
	v_fmamk_f32 v126, v126, 0x3c800000, v195
	v_mul_f32_e32 v127, 0x4b800000, v126
	v_cmp_gt_f32_e32 vcc, s98, v126
	s_nop 1
	v_cndmask_b32_e32 v126, v126, v127, vcc
	v_rsq_f32_e32 v126, v126
	s_nop 0
	v_mul_f32_e32 v127, 0x45800000, v126
	v_cndmask_b32_e32 v140, v126, v127, vcc
	v_pk_mul_f32 v[138:139], v[120:121], v[140:141] op_sel_hi:[1,0]
	v_pk_mul_f32 v[136:137], v[118:119], v[140:141] op_sel_hi:[1,0]
	v_pk_fma_f32 v[134:135], v[110:111], v[138:139], v[114:115]
	v_pk_fma_f32 v[132:133], v[108:109], v[136:137], v[112:113]
	v_pk_fma_f32 v[134:135], v[116:117], v[130:131], v[134:135] op_sel_hi:[0,1,1]
	v_pk_fma_f32 v[132:133], v[116:117], v[128:129], v[132:133] op_sel_hi:[0,1,1]
	v_mul_f32_e32 v132, v70, v132
	v_mul_f32_e32 v133, v71, v133
	v_mul_f32_e32 v134, v72, v134
	v_mul_f32_e32 v135, v73, v135
	v_cvt_pk_bf16_f32 v142, v132, v133
	v_cvt_pk_bf16_f32 v143, v134, v135
	global_store_dwordx2 v101, v[142:143], s[62:63]
	s_add_u32 s62, s62, 0x200000
	s_addc_u32 s63, s63, 0
	s_branch .LBB0_1000
